# attention loop: third score tile in VGPRs, list-rescheduled VALU (lazy fill of MFMA shadows), next-tile K/V address calc + global loads moved into QK MFMA shadows
# speedup vs baseline: 1.0636x; 1.0194x over previous
; template <bool SAMPLE>
; DEV void attn_unit(CParams& p, int layer, int unit, float lam, float lam_init, char* lds, const int swave) {
;   const int tid = ltid(), lane = tid & 63, w = __builtin_amdgcn_readfirstlane(tid >> 6), lr = lane & 31, hh = lane >> 5;
;   char* ws = p.ws;
;   const bf16_t* proj = (const bf16_t*)(ws + W_PROJ);
;   constexpr bool sample = SAMPLE;
;   int b, head, qb = 0, ntiles;
;   if (sample) { b = unit >> 2; head = unit & 3; ntiles = 33; }
;   else { const int u = unit - 32; qb = 127 - (u >> 3); b = (u >> 2) & 1; head = u & 3; ntiles = 2 * qb + 2; }
;   const int my_tiles = sample ? (w == 0 ? 33 : 0) : (w < 2 ? ntiles - 1 : ntiles);
;   int qrow;
;   if (sample) qrow = TP + b * 16 + (lr < 16 ? lr : 15);
;   else qrow = b * 16384 + qb * 128 + w * 32 + lr;
;   bf16x8 qf[2][4];
; #pragma unroll
;   for (int br = 0; br < 2; ++br)
; #pragma unroll
;     for (int ks = 0; ks < 4; ++ks) qf[br][ks] = *(const bf16x8*)(proj + (size_t)qrow * PW + C_Q + head * 128 + br * 64 + ks * 16 + hh * 8);
;   const int krow = tid >> 4, kch = tid & 15;
;   u32x4 rk[4], rv[4];
;   const unsigned voffP = (unsigned)(krow * PW + kch * 8) * 2u;
;   const unsigned voffC = (unsigned)(krow * 512 + kch * 8) * 2u;
;   auto kbase = [&](int t, int i, unsigned& voff, size_t& vdelta) -> const char* {
;     if (sample && t < 32) { voff = voffC; vdelta = W_VC - W_KC; return ws + W_KC + ((size_t)(b * 2048 + t * 64 + 16 * i) * 512 + head * 128) * 2; }
;     voff = voffP; vdelta = (size_t)(C_V - C_K) * 2;
;     if (sample) return (const char*)proj + ((size_t)(TP + b * 16) * PW + C_K + head * 128) * 2;
; __global__ void __launch_bounds__(256) fwd_megakernel(Params p_unused, LamInit li) {
;     ...
;       for (;;) {
;         __syncthreads();
;         if (ltid() == 0) s_unit = (int)atomicAdd((unsigned*)(ws + W_CTR) + layer * 16 + rep * 4, 1u);
;         __syncthreads();
;         const int u = __builtin_amdgcn_readfirstlane(s_unit) + (rep ? NSCAN : 0);
;         if (u >= NSCAN + NATT) break;
;         if (u < 32) ssd_scan_unit(p, layer, u, swave);
;         else if (u < 34) lru_scan_unit(p, layer, u - 32, swave);
;         else if (u < 42) chunk_unit(p, layer, 2, u - 34, 0, lds, swave);
;         else if (u - NSCAN < 32) attn_unit<true>(p, layer, u - NSCAN, lam, li.v[layer], lds, swave);
;         else attn_unit<false>(p, layer, u - NSCAN, lam, li.v[layer], lds, swave);
.LBB0_237:
	s_or_b64 exec, exec, s[2:3]
	s_waitcnt lgkmcnt(0)
	s_barrier
	ds_read_b32 v0, v241
	s_mov_b64 s[2:3], -1
	s_waitcnt lgkmcnt(0)
	v_readfirstlane_b32 s72, v0
	s_cmpk_gt_i32 s72, 0x449
	s_cbranch_scc1 .LBB0_232
	s_cmp_gt_i32 s72, 31
	s_cbranch_scc0 .LBB0_612
	s_cmp_gt_u32 s72, 33
	s_cbranch_scc0 .LBB0_607
	s_cmp_gt_u32 s72, 41
	s_cbranch_scc0 .LBB0_269
	s_load_dwordx2 s[4:5], s[64:65], 0xc0
	s_sub_i32 s15, s72, 42
	s_cmpk_gt_u32 s72, 0x49
	s_cbranch_scc0 .LBB0_250
	v_mov_b32_e32 v0, v241
	s_mov_b32 s3, 0
	v_mbcnt_lo_u32_b32 v0, -1, v0
	v_mbcnt_hi_u32_b32 v49, -1, v0
	v_or_b32_e32 v2, s53, v49
	v_and_b32_e32 v52, 31, v49
	v_readfirstlane_b32 s2, v2
	s_ashr_i32 s30, s2, 6
	s_add_i32 s2, s72, 0xffffffb6
	s_lshr_b32 s2, s2, 3
	s_sub_i32 s2, 0x7f, s2
	s_lshl_b32 s6, s2, 1
	s_add_i32 s23, s6, 2
	s_or_b32 s29, s6, 1
	s_lshl_b32 s6, s15, 12
	s_and_b32 s28, s6, 0x4000
	s_lshl_b32 s2, s2, 7
	s_or_b32 s2, s2, s28
	v_or_b32_e32 v0, s2, v52
	s_lshl_b32 s2, s15, 7
	v_lshl_add_u32 v128, s30, 5, v0
	v_mov_b64_e32 v[0:1], s[68:69]
	s_and_b32 s22, s2, 0x180
	v_bfe_u32 v134, v49, 5, 1
	v_mad_i64_i32 v[0:1], s[6:7], v128, s16, v[0:1]
	s_lshl_b32 s34, s22, 1
	v_lshl_add_u64 v[0:1], v[0:1], 0, s[34:35]
	v_lshlrev_b32_e32 v240, 4, v134
	v_lshl_add_u64 v[0:1], v[0:1], 0, v[240:241]
	global_load_dwordx4 v[16:19], v[0:1], off offset:3072
	global_load_dwordx4 v[20:23], v[0:1], off offset:3104
	global_load_dwordx4 v[24:27], v[0:1], off offset:3136
	global_load_dwordx4 v[28:31], v[0:1], off offset:3168
	global_load_dwordx4 v[32:35], v[0:1], off offset:3200
	global_load_dwordx4 v[36:39], v[0:1], off offset:3232
	global_load_dwordx4 v[40:43], v[0:1], off offset:3264
	global_load_dwordx4 v[44:47], v[0:1], off offset:3296
	v_mov_b32_e32 v0, v241
	v_ashrrev_i32_e32 v53, 4, v2
	s_mul_i32 s6, s28, 0xc00
	v_mov_b32_e32 v1, v0
	v_mov_b32_e32 v2, v0
	v_mov_b32_e32 v3, v0
	v_mov_b32_e32 v4, v0
	v_mov_b32_e32 v5, v0
	v_mov_b32_e32 v6, v0
	v_mov_b32_e32 v7, v0
	v_mov_b32_e32 v8, v0
	v_mov_b32_e32 v9, v0
	v_mov_b32_e32 v10, v0
	v_mov_b32_e32 v11, v0
	v_mov_b32_e32 v12, v0
	v_mov_b32_e32 v13, v0
	v_mov_b32_e32 v14, v0
	v_mov_b32_e32 v15, v0
	v_accvgpr_write_b32 a0, v0
	v_accvgpr_write_b32 a1, v1
	v_accvgpr_write_b32 a2, v2
	v_accvgpr_write_b32 a3, v3
	v_accvgpr_write_b32 a4, v4
	v_accvgpr_write_b32 a5, v5
	v_accvgpr_write_b32 a6, v6
	v_accvgpr_write_b32 a7, v7
	v_accvgpr_write_b32 a8, v8
	v_accvgpr_write_b32 a9, v9
	v_accvgpr_write_b32 a10, v10
	v_accvgpr_write_b32 a11, v11
	v_accvgpr_write_b32 a12, v12
	v_accvgpr_write_b32 a13, v13
	v_accvgpr_write_b32 a14, v14
	v_accvgpr_write_b32 a15, v15
	v_mov_b32_e32 v0, v241
	s_or_b32 s2, s22, 0x800
	v_mov_b32_e32 v15, v0
	v_mov_b32_e32 v1, v0
	v_mov_b32_e32 v2, v0
	v_mov_b32_e32 v3, v0
	v_mov_b32_e32 v4, v0
	v_mov_b32_e32 v5, v0
	v_mov_b32_e32 v6, v0
	v_mov_b32_e32 v7, v0
	v_mov_b32_e32 v8, v0
	v_mov_b32_e32 v9, v0
	v_mov_b32_e32 v10, v0
	v_mov_b32_e32 v11, v0
	v_mov_b32_e32 v12, v0
	v_mov_b32_e32 v13, v0
	v_mov_b32_e32 v14, v0
	v_accvgpr_write_b32 a31, v15
	v_accvgpr_write_b32 a30, v14
	v_accvgpr_write_b32 a29, v13
	v_accvgpr_write_b32 a28, v12
	v_accvgpr_write_b32 a27, v11
	v_accvgpr_write_b32 a26, v10
	v_accvgpr_write_b32 a25, v9
	v_accvgpr_write_b32 a24, v8
	v_accvgpr_write_b32 a23, v7
	v_accvgpr_write_b32 a22, v6
	v_accvgpr_write_b32 a21, v5
	v_accvgpr_write_b32 a20, v4
	v_accvgpr_write_b32 a19, v3
	v_accvgpr_write_b32 a18, v2
	v_accvgpr_write_b32 a17, v1
	v_accvgpr_write_b32 a16, v0
	v_mov_b32_e32 v0, v241
	s_or_b32 s6, s6, s2
	v_mov_b32_e32 v15, v0
	v_mov_b32_e32 v1, v0
	v_mov_b32_e32 v2, v0
	v_mov_b32_e32 v3, v0
	v_mov_b32_e32 v4, v0
	v_mov_b32_e32 v5, v0
	v_mov_b32_e32 v6, v0
	v_mov_b32_e32 v7, v0
	v_mov_b32_e32 v8, v0
	v_mov_b32_e32 v9, v0
	v_mov_b32_e32 v10, v0
	v_mov_b32_e32 v11, v0
	v_mov_b32_e32 v12, v0
	v_mov_b32_e32 v13, v0
	v_mov_b32_e32 v14, v0
	v_accvgpr_write_b32 a47, v15
	v_accvgpr_write_b32 a46, v14
	v_accvgpr_write_b32 a45, v13
	v_accvgpr_write_b32 a44, v12
	v_accvgpr_write_b32 a43, v11
	v_accvgpr_write_b32 a42, v10
	v_accvgpr_write_b32 a41, v9
	v_accvgpr_write_b32 a40, v8
	v_accvgpr_write_b32 a39, v7
	v_accvgpr_write_b32 a38, v6
	v_accvgpr_write_b32 a37, v5
	v_accvgpr_write_b32 a36, v4
	v_accvgpr_write_b32 a35, v3
	v_accvgpr_write_b32 a34, v2
	v_accvgpr_write_b32 a33, v1
	v_accvgpr_write_b32 a32, v0
	v_mov_b32_e32 v0, v241
	s_lshl_b32 s6, s6, 1
	v_mov_b32_e32 v15, v0
	v_mov_b32_e32 v1, v0
	v_mov_b32_e32 v2, v0
	v_mov_b32_e32 v3, v0
	v_mov_b32_e32 v4, v0
	v_mov_b32_e32 v5, v0
	v_mov_b32_e32 v6, v0
	v_mov_b32_e32 v7, v0
	v_mov_b32_e32 v8, v0
	v_mov_b32_e32 v9, v0
	v_mov_b32_e32 v10, v0
	v_mov_b32_e32 v11, v0
	v_mov_b32_e32 v12, v0
	v_mov_b32_e32 v13, v0
	v_mov_b32_e32 v14, v0
	v_accvgpr_write_b32 a63, v15
	v_accvgpr_write_b32 a62, v14
	v_accvgpr_write_b32 a61, v13
	v_accvgpr_write_b32 a60, v12
	v_accvgpr_write_b32 a59, v11
	v_accvgpr_write_b32 a58, v10
	v_accvgpr_write_b32 a57, v9
	v_accvgpr_write_b32 a56, v8
	v_accvgpr_write_b32 a55, v7
	v_accvgpr_write_b32 a54, v6
	v_accvgpr_write_b32 a53, v5
	v_accvgpr_write_b32 a52, v4
	v_accvgpr_write_b32 a51, v3
	v_accvgpr_write_b32 a50, v2
	v_accvgpr_write_b32 a49, v1
	v_accvgpr_write_b32 a48, v0
	v_mov_b32_e32 v0, v241
	s_add_u32 s60, s68, s6
	v_mov_b32_e32 v15, v0
	v_mov_b32_e32 v1, v0
	v_mov_b32_e32 v2, v0
	v_mov_b32_e32 v3, v0
	v_mov_b32_e32 v4, v0
	v_mov_b32_e32 v5, v0
	v_mov_b32_e32 v6, v0
	v_mov_b32_e32 v7, v0
	v_mov_b32_e32 v8, v0
	v_mov_b32_e32 v9, v0
	v_mov_b32_e32 v10, v0
	v_mov_b32_e32 v11, v0
	v_mov_b32_e32 v12, v0
	v_mov_b32_e32 v13, v0
	v_mov_b32_e32 v14, v0
	v_accvgpr_write_b32 a79, v15
	v_accvgpr_write_b32 a78, v14
	v_accvgpr_write_b32 a77, v13
; DEV f32x16 zero16() { float zz = 0.f; asm volatile("" : "+v"(zz)); f32x16 z; for (int i = 0; i < 16; ++i) z[i] = zz; return z; }
; template <bool SAMPLE>
; DEV void attn_unit(CParams& p, int layer, int unit, float lam, float lam_init, char* lds, const int swave) {
;     ...
;   const int krow = tid >> 4, kch = tid & 15;
;   u32x4 rk[4], rv[4];
;   const unsigned voffP = (unsigned)(krow * PW + kch * 8) * 2u;
;   const unsigned voffC = (unsigned)(krow * 512 + kch * 8) * 2u;
;   auto kbase = [&](int t, int i, unsigned& voff, size_t& vdelta) -> const char* {
;     if (sample && t < 32) { voff = voffC; vdelta = W_VC - W_KC; return ws + W_KC + ((size_t)(b * 2048 + t * 64 + 16 * i) * 512 + head * 128) * 2; }
;     voff = voffP; vdelta = (size_t)(C_V - C_K) * 2;
;     if (sample) return (const char*)proj + ((size_t)(TP + b * 16) * PW + C_K + head * 128) * 2;
;     return (const char*)proj + ((size_t)(b * 16384 + t * 64 + 16 * i) * PW + C_K + head * 128) * 2;
;   };
;   auto gloadK = [&](int t) {
; #pragma unroll
;     for (int i = 0; i < 4; ++i) { unsigned voff; size_t vd; const char* kb = kbase(t, i, voff, vd); rk[i] = *(const u32x4*)(kb + voff); }
;   };
;   auto gloadV = [&](int t) {
; #pragma unroll
;     for (int i = 0; i < 4; ++i) { unsigned voff; size_t vd; const char* kb = kbase(t, i, voff, vd); rv[i] = *(const u32x4*)(kb + vd + voff); }
;   };
;   auto lwrite = [&](int buf) {
;     char* ks_ = lds + buf * A_BUF; char* vs_ = ks_ + A_KT;
; #pragma unroll
;     for (int i = 0; i < 4; ++i) {
;       const int r = krow + 16 * i;
;       *(u32x4*)(ks_ + r * AK_B + kch * 16) = rk[i];
;       *(u32x4*)(vs_ + r * AV_B + kch * 16) = rv[i];
;     }
;   };
;   f32x16 O1[4], O2[4];
; #pragma unroll
;   for (int e = 0; e < 4; ++e) { O1[e] = zero16(); O2[e] = zero16(); }
;   float ls[2] = {0.f, 0.f};
;   const float cexp = 0.125f * 1.4426950408889634f;
;   gloadK(0); gloadV(0); lwrite(0); __syncthreads();
	v_accvgpr_write_b32 a76, v12
	v_accvgpr_write_b32 a75, v11
	v_accvgpr_write_b32 a74, v10
	v_accvgpr_write_b32 a73, v9
	v_accvgpr_write_b32 a72, v8
	v_accvgpr_write_b32 a71, v7
	v_accvgpr_write_b32 a70, v6
	v_accvgpr_write_b32 a69, v5
	v_accvgpr_write_b32 a68, v4
	v_accvgpr_write_b32 a67, v3
	v_accvgpr_write_b32 a66, v2
	v_accvgpr_write_b32 a65, v1
	v_accvgpr_write_b32 a64, v0
	v_mov_b32_e32 v0, v241
	s_addc_u32 s61, s69, 0
	v_mov_b32_e32 v15, v0
	v_mov_b32_e32 v1, v0
	v_mov_b32_e32 v2, v0
	v_mov_b32_e32 v3, v0
	v_mov_b32_e32 v4, v0
	v_mov_b32_e32 v5, v0
	v_mov_b32_e32 v6, v0
	v_mov_b32_e32 v7, v0
	v_mov_b32_e32 v8, v0
	v_mov_b32_e32 v9, v0
	v_mov_b32_e32 v10, v0
	v_mov_b32_e32 v11, v0
	v_mov_b32_e32 v12, v0
	v_mov_b32_e32 v13, v0
	v_mov_b32_e32 v14, v0
	v_accvgpr_write_b32 a95, v15
	s_or_b32 s7, s6, 0x18000
	v_accvgpr_write_b32 a94, v14
	v_accvgpr_write_b32 a93, v13
	v_accvgpr_write_b32 a92, v12
	v_accvgpr_write_b32 a91, v11
	v_accvgpr_write_b32 a90, v10
	v_accvgpr_write_b32 a89, v9
	v_accvgpr_write_b32 a88, v8
	v_accvgpr_write_b32 a87, v7
	v_accvgpr_write_b32 a86, v6
	v_accvgpr_write_b32 a85, v5
	v_accvgpr_write_b32 a84, v4
	v_accvgpr_write_b32 a83, v3
	v_accvgpr_write_b32 a82, v2
	v_accvgpr_write_b32 a81, v1
	v_accvgpr_write_b32 a80, v0
	v_mov_b32_e32 v0, v241
	s_add_u32 s56, s68, s7
	s_addc_u32 s57, s69, 0
	v_mov_b32_e32 v15, v0
	s_or_b32 s7, s6, 0x30000
	v_mov_b32_e32 v1, v0
	v_mov_b32_e32 v2, v0
	v_mov_b32_e32 v3, v0
	v_mov_b32_e32 v4, v0
	v_mov_b32_e32 v5, v0
	v_mov_b32_e32 v6, v0
	v_mov_b32_e32 v7, v0
	v_mov_b32_e32 v8, v0
	v_mov_b32_e32 v9, v0
	v_mov_b32_e32 v10, v0
	v_mov_b32_e32 v11, v0
	v_mov_b32_e32 v12, v0
	v_mov_b32_e32 v13, v0
	v_mov_b32_e32 v14, v0
	v_accvgpr_write_b32 a111, v15
	s_add_u32 s8, s68, s7
	v_lshlrev_b32_e32 v50, 4, v49
	v_accvgpr_write_b32 a110, v14
	v_accvgpr_write_b32 a109, v13
	v_accvgpr_write_b32 a108, v12
	v_accvgpr_write_b32 a107, v11
	v_accvgpr_write_b32 a106, v10
	v_accvgpr_write_b32 a105, v9
	v_accvgpr_write_b32 a104, v8
	v_accvgpr_write_b32 a103, v7
	v_accvgpr_write_b32 a102, v6
	v_accvgpr_write_b32 a101, v5
	v_accvgpr_write_b32 a100, v4
	v_accvgpr_write_b32 a99, v3
	v_accvgpr_write_b32 a98, v2
	v_accvgpr_write_b32 a97, v1
	v_accvgpr_write_b32 a96, v0
	v_mov_b32_e32 v0, v241
	s_addc_u32 s9, s69, 0
	s_or_b32 s6, s6, 0x48000
	v_mul_lo_u32 v51, v53, s16
	v_and_b32_e32 v76, 0xf0, v50
	v_mov_b32_e32 v15, v0
	s_add_u32 s6, s68, s6
	v_mov_b32_e32 v1, v0
	v_mov_b32_e32 v2, v0
	v_mov_b32_e32 v3, v0
	v_mov_b32_e32 v4, v0
	v_mov_b32_e32 v5, v0
	v_mov_b32_e32 v6, v0
	v_mov_b32_e32 v7, v0
	v_mov_b32_e32 v8, v0
	v_mov_b32_e32 v9, v0
	v_mov_b32_e32 v10, v0
	v_mov_b32_e32 v11, v0
	v_mov_b32_e32 v12, v0
	v_mov_b32_e32 v13, v0
	v_mov_b32_e32 v14, v0
	v_accvgpr_write_b32 a127, v15
	v_or_b32_e32 v50, v51, v76
	s_addc_u32 s7, s69, 0
	v_accvgpr_write_b32 a126, v14
	v_accvgpr_write_b32 a125, v13
	v_accvgpr_write_b32 a124, v12
	v_accvgpr_write_b32 a123, v11
	v_accvgpr_write_b32 a122, v10
	v_accvgpr_write_b32 a121, v9
	v_accvgpr_write_b32 a120, v8
	v_accvgpr_write_b32 a119, v7
	v_accvgpr_write_b32 a118, v6
	v_accvgpr_write_b32 a117, v5
	v_accvgpr_write_b32 a116, v4
	v_accvgpr_write_b32 a115, v3
	v_accvgpr_write_b32 a114, v2
	v_accvgpr_write_b32 a113, v1
	v_accvgpr_write_b32 a112, v0
	global_load_dwordx4 v[12:15], v50, s[60:61]
	global_load_dwordx4 v[8:11], v50, s[56:57]
	global_load_dwordx4 v[4:7], v50, s[8:9]
	global_load_dwordx4 v[0:3], v50, s[6:7]
	global_load_dwordx4 v[70:73], v50, s[60:61] offset:1024
	global_load_dwordx4 v[88:91], v50, s[56:57] offset:1024
	global_load_dwordx4 v[92:95], v50, s[8:9] offset:1024
	global_load_dwordx4 v[96:99], v50, s[6:7] offset:1024
	s_movk_i32 s6, 0x110
	v_mul_lo_u32 v77, v53, s6
	v_add3_u32 v54, 16, v77, v76
	s_movk_i32 s6, 0x140
	v_mul_lo_u32 v78, v53, s6
	s_movk_i32 s6, 0x1100
	v_mul_u32_u24_e32 v85, 0x110, v52
	v_and_b32_e32 v48, 63, v49
	s_cmp_lt_i32 s30, 2
	v_mov_b32_e32 v51, v241
	v_ashrrev_i32_e32 v129, 31, v128
	v_add_u32_e32 v79, 0x1100, v77
	v_add_u32_e32 v80, 0x1400, v78
	v_add_u32_e32 v81, 0x2200, v77
	v_add_u32_e32 v82, 0x2800, v78
	v_add_u32_e32 v83, 0x3300, v77
	v_add_u32_e32 v84, 0x3c00, v78
	s_cselect_b32 s29, s29, s23
	s_or_b32 s30, s28, 16
	s_or_b32 s31, s28, 32
	s_or_b32 s34, s28, 48
	v_lshl_add_u64 v[50:51], s[68:69], 0, v[50:51]
	v_mov_b32_e32 v130, v241
	v_mov_b32_e32 v131, v241
	s_mov_b32 s37, s3
	s_waitcnt vmcnt(7)
	ds_write_b128 v54, v[12:15]
	v_mul_lo_u32 v12, v53, 48
	v_add_u32_e32 v13, v54, v12
	v_mov_b32_e32 v14, v241
	s_waitcnt vmcnt(3)
	ds_write_b128 v13, v[70:73] offset:17408
	ds_write_b128 v54, v[8:11] offset:4352
	v_add3_u32 v8, v54, s6, v12
	s_movk_i32 s6, 0x2200
	s_waitcnt vmcnt(2)
	ds_write_b128 v8, v[88:91] offset:18176
	ds_write_b128 v54, v[4:7] offset:8704
	v_add3_u32 v4, v54, s6, v12
	s_movk_i32 s6, 0x3300
	s_waitcnt vmcnt(1)
	ds_write_b128 v4, v[92:95] offset:18944
	ds_write_b128 v54, v[0:3] offset:13056
	v_add3_u32 v0, v54, s6, v12
	v_mov_b32_e32 v15, v241
	v_add3_u32 v13, 16, v85, v240
	s_waitcnt vmcnt(0)
	ds_write_b128 v0, v[96:99] offset:19712
	s_waitcnt lgkmcnt(0)
	s_barrier
; DEV f32x16 mfma32(bf16x8 a, bf16x8 b, f32x16 c) { return __builtin_amdgcn_mfma_f32_32x32x16_bf16(a, b, c, 0, 0, 0); }
; DEV f32x16 zero16() { float zz = 0.f; asm volatile("" : "+v"(zz)); f32x16 z; for (int i = 0; i < 16; ++i) z[i] = zz; return z; }
; DEV float shx(float v, int o, int lane) { return __builtin_bit_cast(float, __builtin_amdgcn_ds_bpermute((lane ^ o) << 2, __builtin_bit_cast(int, v))); }
; template <bool SAMPLE>
; DEV void attn_unit(CParams& p, int layer, int unit, float lam, float lam_init, char* lds, const int swave) {
;     ...
;   float nmc[2] = {0.f, 0.f};
;   if (my_tiles > 0) {
; #pragma unroll
;     for (int br = 0; br < 2; ++br) {
;       f32x16 S0 = zero16(), S1 = zero16();
; #pragma unroll
;       for (int ks = 0; ks < 4; ++ks) {
;         const bf16x8 k0 = lds_read8(lds + lr * AK_B + (br * 64 + ks * 16 + hh * 8) * 2);
;         const bf16x8 k1 = lds_read8(lds + (32 + lr) * AK_B + (br * 64 + ks * 16 + hh * 8) * 2);
;         S0 = mfma32(k0, qf[br][ks], S0); S1 = mfma32(k1, qf[br][ks], S1);
;       }
;       float m = S0[0];
; #pragma unroll
;       for (int r = 1; r < 16; ++r) m = fmaxf(m, S0[r]);
; #pragma unroll
;       for (int r = 0; r < 16; ++r) m = fmaxf(m, S1[r]);
;       m = fmaxf(m, shx(m, 32, lane));
;       nmc[br] = -m * cexp;
;     }
	ds_read_b128 v[4:7], v13 offset:8704
	ds_read_b128 v[0:3], v13
	ds_read_b128 v[8:11], v13 offset:32
	v_accvgpr_write_b32 a128, v14
	v_accvgpr_write_b32 a129, v14
	v_accvgpr_write_b32 a130, v14
	v_accvgpr_write_b32 a131, v14
	v_accvgpr_write_b32 a132, v14
	v_accvgpr_write_b32 a133, v14
	v_accvgpr_write_b32 a134, v14
	v_accvgpr_write_b32 a135, v14
	v_accvgpr_write_b32 a136, v14
	v_accvgpr_write_b32 a137, v14
	v_accvgpr_write_b32 a138, v14
	v_accvgpr_write_b32 a139, v14
	v_accvgpr_write_b32 a140, v14
	v_accvgpr_write_b32 a141, v14
	v_accvgpr_write_b32 a142, v14
	v_accvgpr_write_b32 a143, v14
	v_lshlrev_b32_e32 v12, 2, v48
	v_xor_b32_e32 v135, 0x80, v12
	s_waitcnt lgkmcnt(1)
	v_mfma_f32_32x32x16_bf16 a[128:143], v[0:3], v[16:19], a[128:143]
	ds_read_b128 v[0:3], v13 offset:8736
	s_waitcnt lgkmcnt(1)
	v_mfma_f32_32x32x16_bf16 a[128:143], v[8:11], v[20:23], a[128:143]
	ds_read_b128 v[52:55], v13 offset:64
	ds_read_b128 v[8:11], v13 offset:8768
	s_waitcnt lgkmcnt(1)
	v_mfma_f32_32x32x16_bf16 a[128:143], v[52:55], v[24:27], a[128:143]
	ds_read_b128 v[52:55], v13 offset:96
	ds_read_b128 v[56:59], v13 offset:8800
	s_waitcnt lgkmcnt(1)
	v_mfma_f32_32x32x16_bf16 a[128:143], v[52:55], v[28:31], a[128:143]
	s_nop 11
	v_accvgpr_read_b32 v14, a128
	v_accvgpr_read_b32 v48, a129
	v_max_f32_e32 v48, v48, v48
	v_max_f32_e32 v14, v14, v14
	v_max_f32_e32 v14, v14, v48
	v_accvgpr_read_b32 v48, a130
	v_accvgpr_read_b32 v52, a131
	v_max3_f32 v14, v14, v48, v52
	v_accvgpr_read_b32 v48, a132
	v_accvgpr_read_b32 v52, a133
	v_max3_f32 v14, v14, v48, v52
	v_accvgpr_read_b32 v48, a134
	v_accvgpr_read_b32 v52, a135
	v_max3_f32 v14, v14, v48, v52
	v_accvgpr_read_b32 v48, a136
	v_accvgpr_read_b32 v52, a137
	v_max3_f32 v14, v14, v48, v52
	v_accvgpr_read_b32 v48, a138
	v_accvgpr_read_b32 v52, a139
	v_max3_f32 v14, v14, v48, v52
	v_accvgpr_read_b32 v48, a140
	v_accvgpr_read_b32 v52, a141
	v_max3_f32 v14, v14, v48, v52
	v_accvgpr_read_b32 v48, a142
	v_accvgpr_read_b32 v52, a143
	v_accvgpr_write_b32 a128, v15
	v_accvgpr_write_b32 a129, v15
	v_accvgpr_write_b32 a130, v15
	v_accvgpr_write_b32 a131, v15
	v_accvgpr_write_b32 a132, v15
	v_accvgpr_write_b32 a133, v15
	v_accvgpr_write_b32 a134, v15
	v_accvgpr_write_b32 a135, v15
	v_accvgpr_write_b32 a136, v15
	v_accvgpr_write_b32 a137, v15
	v_accvgpr_write_b32 a138, v15
	v_accvgpr_write_b32 a139, v15
	v_accvgpr_write_b32 a140, v15
	v_accvgpr_write_b32 a141, v15
	v_accvgpr_write_b32 a142, v15
	v_accvgpr_write_b32 a143, v15
	v_max3_f32 v14, v14, v48, v52
	v_mov_b32_e32 v15, v241
	v_mfma_f32_32x32x16_bf16 a[128:143], v[4:7], v[16:19], a[128:143]
	v_mfma_f32_32x32x16_bf16 a[128:143], v[0:3], v[20:23], a[128:143]
	v_mfma_f32_32x32x16_bf16 a[128:143], v[8:11], v[24:27], a[128:143]
	s_waitcnt lgkmcnt(0)
	v_mfma_f32_32x32x16_bf16 a[128:143], v[56:59], v[28:31], a[128:143]
	s_nop 11
	v_accvgpr_read_b32 v0, a128
	v_accvgpr_read_b32 v1, a129
	v_max3_f32 v0, v14, v0, v1
	v_accvgpr_read_b32 v1, a130
	v_accvgpr_read_b32 v2, a131
	v_max3_f32 v0, v0, v1, v2
	v_accvgpr_read_b32 v1, a132
	v_accvgpr_read_b32 v2, a133
	v_max3_f32 v0, v0, v1, v2
	v_accvgpr_read_b32 v1, a134
	v_accvgpr_read_b32 v2, a135
	v_max3_f32 v0, v0, v1, v2
	v_accvgpr_read_b32 v1, a136
	v_accvgpr_read_b32 v2, a137
	v_max3_f32 v0, v0, v1, v2
	v_accvgpr_read_b32 v1, a138
	v_accvgpr_read_b32 v2, a139
	v_max3_f32 v0, v0, v1, v2
	v_accvgpr_read_b32 v1, a140
	v_accvgpr_read_b32 v2, a141
	v_max3_f32 v0, v0, v1, v2
	v_accvgpr_read_b32 v1, a142
	v_accvgpr_read_b32 v2, a143
	v_max3_f32 v0, v0, v1, v2
	ds_bpermute_b32 v1, v135, v0
	v_mov_b32_e32 v14, v241
	s_waitcnt lgkmcnt(0)
	v_max_f32_e32 v1, v1, v1
	v_max_f32_e32 v0, v0, v1
	v_mul_f32_e32 v48, 0xbe38aa3b, v0
	ds_read_b128 v[4:7], v13 offset:8832
	ds_read_b128 v[0:3], v13 offset:128
	ds_read_b128 v[8:11], v13 offset:160
	v_accvgpr_write_b32 a128, v14
	v_accvgpr_write_b32 a129, v14
	v_accvgpr_write_b32 a130, v14
	v_accvgpr_write_b32 a131, v14
	v_accvgpr_write_b32 a132, v14
	v_accvgpr_write_b32 a133, v14
	v_accvgpr_write_b32 a134, v14
	v_accvgpr_write_b32 a135, v14
	v_accvgpr_write_b32 a136, v14
	v_accvgpr_write_b32 a137, v14
	v_accvgpr_write_b32 a138, v14
	v_accvgpr_write_b32 a139, v14
	v_accvgpr_write_b32 a140, v14
	v_accvgpr_write_b32 a141, v14
	v_accvgpr_write_b32 a142, v14
	v_accvgpr_write_b32 a143, v14
	s_waitcnt lgkmcnt(1)
	s_nop 0
	v_mfma_f32_32x32x16_bf16 a[128:143], v[0:3], v[32:35], a[128:143]
	ds_read_b128 v[0:3], v13 offset:8864
	s_waitcnt lgkmcnt(1)
	v_mfma_f32_32x32x16_bf16 a[128:143], v[8:11], v[36:39], a[128:143]
	ds_read_b128 v[52:55], v13 offset:192
	ds_read_b128 v[8:11], v13 offset:8896
	s_waitcnt lgkmcnt(1)
	v_mfma_f32_32x32x16_bf16 a[128:143], v[52:55], v[40:43], a[128:143]
	ds_read_b128 v[52:55], v13 offset:224
	ds_read_b128 v[56:59], v13 offset:8928
	s_waitcnt lgkmcnt(1)
	v_mfma_f32_32x32x16_bf16 a[128:143], v[52:55], v[44:47], a[128:143]
	s_nop 11
	v_accvgpr_read_b32 v13, a128
	v_accvgpr_read_b32 v14, a129
	v_max_f32_e32 v14, v14, v14
	v_max_f32_e32 v13, v13, v13
	v_max_f32_e32 v13, v13, v14
	v_accvgpr_read_b32 v14, a130
	v_accvgpr_read_b32 v52, a131
	v_max3_f32 v13, v13, v14, v52
	v_accvgpr_read_b32 v14, a132
	v_accvgpr_read_b32 v52, a133
	v_max3_f32 v13, v13, v14, v52
	v_accvgpr_read_b32 v14, a134
	v_accvgpr_read_b32 v52, a135
	v_max3_f32 v13, v13, v14, v52
	v_accvgpr_read_b32 v14, a136
	v_accvgpr_read_b32 v52, a137
	v_max3_f32 v13, v13, v14, v52
	v_accvgpr_read_b32 v14, a138
	v_accvgpr_read_b32 v52, a139
	v_max3_f32 v13, v13, v14, v52
	v_accvgpr_read_b32 v14, a140
	v_accvgpr_read_b32 v52, a141
	v_max3_f32 v13, v13, v14, v52
	v_accvgpr_read_b32 v14, a142
	v_accvgpr_read_b32 v52, a143
	v_accvgpr_write_b32 a128, v15
	v_accvgpr_write_b32 a129, v15
	v_accvgpr_write_b32 a130, v15
	v_accvgpr_write_b32 a131, v15
	v_accvgpr_write_b32 a132, v15
	v_accvgpr_write_b32 a133, v15
	v_accvgpr_write_b32 a134, v15
	v_accvgpr_write_b32 a135, v15
	v_accvgpr_write_b32 a136, v15
	v_accvgpr_write_b32 a137, v15
	v_accvgpr_write_b32 a138, v15
	v_accvgpr_write_b32 a139, v15
	v_accvgpr_write_b32 a140, v15
	v_accvgpr_write_b32 a141, v15
	v_accvgpr_write_b32 a142, v15
	v_accvgpr_write_b32 a143, v15
	v_max3_f32 v13, v13, v14, v52
	s_nop 0
	v_mfma_f32_32x32x16_bf16 a[128:143], v[4:7], v[32:35], a[128:143]
	v_mfma_f32_32x32x16_bf16 a[128:143], v[0:3], v[36:39], a[128:143]
	v_mfma_f32_32x32x16_bf16 a[128:143], v[8:11], v[40:43], a[128:143]
	s_waitcnt lgkmcnt(0)
; DEV f32x16 mfma32(bf16x8 a, bf16x8 b, f32x16 c) { return __builtin_amdgcn_mfma_f32_32x32x16_bf16(a, b, c, 0, 0, 0); }
; DEV float shx(float v, int o, int lane) { return __builtin_bit_cast(float, __builtin_amdgcn_ds_bpermute((lane ^ o) << 2, __builtin_bit_cast(int, v))); }
; template <bool SAMPLE>
; DEV void attn_unit(CParams& p, int layer, int unit, float lam, float lam_init, char* lds, const int swave) {
;     ...
;       for (int r = 1; r < 16; ++r) m = fmaxf(m, S0[r]);
; #pragma unroll
;       for (int r = 0; r < 16; ++r) m = fmaxf(m, S1[r]);
;       m = fmaxf(m, shx(m, 32, lane));
;       nmc[br] = -m * cexp;
;     }
;   }
;   for (int t = 0; t < ntiles; ++t) {
;     const int tn = SAMPLE ? t + 1 : (t + 1 < ntiles ? t + 1 : t);
;     if (!SAMPLE || t + 1 < ntiles) gloadK(tn);
;     if (t < my_tiles) {
;       const char* Ks = lds + (t & 1) * A_BUF; const char* Vs = Ks + A_KT;
;       bf16x8 pf[2][4];
;       f32x16 S0, S1;
;       auto qk = [&](int br) {
;         const f32x16 zc = {0.f, 0.f, 0.f, 0.f, 0.f, 0.f, 0.f, 0.f, 0.f, 0.f, 0.f, 0.f, 0.f, 0.f, 0.f, 0.f};
; #pragma unroll
;         for (int ks = 0; ks < 4; ++ks) {
;           const bf16x8 k0 = lds_read8(Ks + lr * AK_B + (br * 64 + ks * 16 + hh * 8) * 2);
;           const bf16x8 k1 = lds_read8(Ks + (32 + lr) * AK_B + (br * 64 + ks * 16 + hh * 8) * 2);
;           S0 = mfma32(k0, qf[br][ks], ks == 0 ? zc : S0); S1 = mfma32(k1, qf[br][ks], ks == 0 ? zc : S1);
;         }
	v_mfma_f32_32x32x16_bf16 a[128:143], v[56:59], v[44:47], a[128:143]
	s_nop 11
	v_accvgpr_read_b32 v0, a128
	v_accvgpr_read_b32 v1, a129
	v_max3_f32 v0, v13, v0, v1
	v_accvgpr_read_b32 v1, a130
	v_accvgpr_read_b32 v2, a131
	v_max3_f32 v0, v0, v1, v2
	v_accvgpr_read_b32 v1, a132
	v_accvgpr_read_b32 v2, a133
	v_max3_f32 v0, v0, v1, v2
	v_accvgpr_read_b32 v1, a134
	v_accvgpr_read_b32 v2, a135
	v_max3_f32 v0, v0, v1, v2
	v_accvgpr_read_b32 v1, a136
	v_accvgpr_read_b32 v2, a137
	v_max3_f32 v0, v0, v1, v2
	v_accvgpr_read_b32 v1, a138
	v_accvgpr_read_b32 v2, a139
	v_max3_f32 v0, v0, v1, v2
	v_accvgpr_read_b32 v1, a140
	v_accvgpr_read_b32 v2, a141
	v_max3_f32 v0, v0, v1, v2
	v_accvgpr_read_b32 v1, a142
	v_accvgpr_read_b32 v2, a143
	v_max3_f32 v0, v0, v1, v2
	ds_bpermute_b32 v1, v135, v0
	s_waitcnt lgkmcnt(0)
	v_max_f32_e32 v1, v1, v1
	v_max_f32_e32 v0, v0, v1
	v_mul_f32_e32 v52, 0xbe38aa3b, v0
	v_bfe_u32 v0, v49, 2, 2
	v_lshrrev_b32_e32 v1, 3, v49
	v_and_or_b32 v0, v1, 4, v0
	v_and_b32_e32 v1, 16, v49
	v_and_or_b32 v1, v12, 12, v1
	v_mov_b32_e32 v49, v48
	v_mov_b32_e32 v53, v52
	v_lshlrev_b32_e32 v86, 1, v1
	v_mul_u32_u24_e32 v87, 0x140, v0
	v_add_u32_e32 v243, v85, v240
	v_mov_b32_e32 v244, v240
.LBB0_243:
	s_add_i32 s36, s37, 1
	s_cmp_ge_u32 s36, s23
	s_cselect_b64 s[6:7], -1, 0
	s_cmp_lt_u32 s36, s23
	s_cselect_b32 s100, s36, s37
	s_lshl_b32 s101, s100, 6
	s_cmp_ge_u32 s37, s29
	s_cbranch_scc1 .LBB0_245
	s_bitcmp1_b32 s37, 0
	s_cselect_b32 s38, 0x9400, 0
	s_add_i32 s38, s38, 16
	v_add_u32_e32 v118, s38, v243
	ds_read_b128 v[62:65], v118
	ds_read_b128 v[66:69], v118 offset:32
	s_waitcnt lgkmcnt(1)
	v_mfma_f32_32x32x16_bf16 v[178:193], v[62:65], v[16:19], 0
	s_add_i32 s8, s101, s28
	s_mul_hi_i32 s9, s8, 0xc00
	s_mulk_i32 s8, 0xc00
	s_or_b64 s[8:9], s[8:9], s[2:3]
	v_lshl_add_u64 v[54:55], s[8:9], 1, v[50:51]
	global_load_dwordx4 v[4:7], v[54:55], off
	global_load_dwordx4 v[194:197], v[54:55], off offset:1024
	ds_read_b128 v[62:65], v118 offset:8704
	ds_read_b128 v[70:73], v118 offset:8736
	s_waitcnt lgkmcnt(1)
	v_mfma_f32_32x32x16_bf16 v[210:225], v[62:65], v[16:19], 0
	s_add_i32 s8, s30, s101
	s_mul_hi_i32 s9, s8, 0xc00
	s_mulk_i32 s8, 0xc00
	s_or_b64 s[8:9], s[8:9], s[2:3]
	v_lshl_add_u64 v[56:57], s[8:9], 1, v[50:51]
	global_load_dwordx4 v[0:3], v[56:57], off
	global_load_dwordx4 v[198:201], v[56:57], off offset:1024
	v_mfma_f32_32x32x16_bf16 v[178:193], v[66:69], v[20:23], v[178:193]
	s_add_i32 s8, s31, s101
	s_mul_hi_i32 s9, s8, 0xc00
	s_mulk_i32 s8, 0xc00
	s_or_b64 s[8:9], s[8:9], s[2:3]
	v_lshl_add_u64 v[58:59], s[8:9], 1, v[50:51]
	global_load_dwordx4 v[12:15], v[58:59], off
	global_load_dwordx4 v[202:205], v[58:59], off offset:1024
	ds_read_b128 v[62:65], v118 offset:64
	ds_read_b128 v[66:69], v118 offset:96
	s_waitcnt lgkmcnt(2)
	v_mfma_f32_32x32x16_bf16 v[210:225], v[70:73], v[20:23], v[210:225]
	s_add_i32 s8, s34, s101
	s_mul_hi_i32 s9, s8, 0xc00
	s_mulk_i32 s8, 0xc00
	s_or_b64 s[8:9], s[8:9], s[2:3]
	v_lshl_add_u64 v[60:61], s[8:9], 1, v[50:51]
	global_load_dwordx4 v[8:11], v[60:61], off
	global_load_dwordx4 v[206:209], v[60:61], off offset:1024
	s_waitcnt lgkmcnt(1)
	v_mfma_f32_32x32x16_bf16 v[178:193], v[62:65], v[24:27], v[178:193]
	ds_read_b128 v[62:65], v118 offset:8768
	ds_read_b128 v[70:73], v118 offset:8800
	ds_read_b128 v[88:91], v118 offset:128
	s_waitcnt lgkmcnt(2)
	v_mfma_f32_32x32x16_bf16 v[210:225], v[62:65], v[24:27], v[210:225]
	s_waitcnt lgkmcnt(0)
	v_mfma_f32_32x32x16_bf16 v[226:241], v[88:91], v[32:35], 0
	v_mfma_f32_32x32x16_bf16 v[178:193], v[66:69], v[28:31], v[178:193]
	s_nop 11
	v_fma_f32 v102, v180, s52, v48
	v_fma_f32 v103, v181, s52, v49
	v_fma_f32 v62, v184, s52, v48
	v_fma_f32 v63, v185, s52, v49
	v_fma_f32 v66, v190, s52, v48
	v_fma_f32 v67, v191, s52, v49
	v_mfma_f32_32x32x16_bf16 v[210:225], v[70:73], v[28:31], v[210:225]
	ds_read_b128 v[68:71], v118 offset:8832
	ds_read_b128 v[92:95], v118 offset:160
	ds_read_b128 v[88:91], v118 offset:8864
	s_waitcnt lgkmcnt(2)
	v_exp_f32_e32 v66, v66
	v_mfma_f32_32x32x16_bf16 a[128:143], v[68:71], v[32:35], 0
	s_waitcnt lgkmcnt(1)
	v_exp_f32_e32 v67, v67
	v_fma_f32 v64, v192, s52, v48
	v_fma_f32 v65, v193, s52, v49
	s_nop 1
	v_fma_f32 v74, v218, s52, v48
	v_mfma_f32_32x32x16_bf16 v[226:241], v[92:95], v[36:39], v[226:241]
	ds_read_b128 v[92:95], v118 offset:192
	s_waitcnt lgkmcnt(1)
	v_fma_f32 v75, v219, s52, v49
	v_fma_f32 v72, v220, s52, v48
	v_fma_f32 v73, v221, s52, v49
	v_exp_f32_e32 v74, v74
	v_mfma_f32_32x32x16_bf16 a[128:143], v[88:91], v[36:39], a[128:143]
	v_fma_f32 v88, v178, s52, v48
	v_fma_f32 v89, v179, s52, v49
	v_exp_f32_e32 v100, v88
	v_exp_f32_e32 v101, v89
	ds_read_b128 v[88:91], v118 offset:8896
	ds_read_b128 v[96:99], v118 offset:224
	s_waitcnt lgkmcnt(2)
	v_mfma_f32_32x32x16_bf16 v[226:241], v[92:95], v[40:43], v[226:241]
	v_exp_f32_e32 v94, v102
	v_exp_f32_e32 v95, v103
	v_cvt_pk_bf16_f32 v92, v100, v101
	v_add_f32_e32 v116, v94, v100
	v_add_f32_e32 v117, v95, v101
	ds_read_b128 v[100:103], v118 offset:8928
	s_waitcnt lgkmcnt(2)
	v_mfma_f32_32x32x16_bf16 a[128:143], v[88:91], v[40:43], a[128:143]
	v_add3_u32 v108, s38, v87, v86
	v_fma_f32 v88, v182, s52, v48
	v_fma_f32 v89, v183, s52, v49
	v_exp_f32_e32 v90, v62
	v_exp_f32_e32 v88, v88
	v_exp_f32_e32 v89, v89
	v_exp_f32_e32 v91, v63
	v_add_f32_e32 v62, v88, v116
	v_add_f32_e32 v63, v89, v117
	ds_read_b64_tr_b16 v[116:117], v108 offset:17408
	ds_read_b64_tr_b16 v[118:119], v108 offset:19968
	s_waitcnt lgkmcnt(2)
; DEV uint32_t pk2(float lo, float hi) { f32x2 v; v[0] = lo; v[1] = hi; bf16v2 b = __builtin_convertvector(v, bf16v2); return __builtin_bit_cast(uint32_t, b); }
; DEV f32x16 mfma32(bf16x8 a, bf16x8 b, f32x16 c) { return __builtin_amdgcn_mfma_f32_32x32x16_bf16(a, b, c, 0, 0, 0); }
; template <bool SAMPLE>
; DEV void attn_unit(CParams& p, int layer, int unit, float lam, float lam_init, char* lds, const int swave) {
;     ...
;       auto sm8 = [&](const f32x16& Sx, int r0, float nm, float& lsum) -> bf16x8 {
;         f32x2 c2; c2[0] = cexp; c2[1] = cexp;
;         f32x2 nm2; nm2[0] = nm; nm2[1] = nm;
;         union { u32x4 u; bf16x8 b; } x;
;         f32x2 sum2; sum2[0] = 0.f; sum2[1] = 0.f;
; #pragma unroll
;         for (int r = 0; r < 8; r += 2) {
;           f32x2 v; v[0] = Sx[r0 + r]; v[1] = Sx[r0 + r + 1];
;           v = v * c2 + nm2;
;           f32x2 ex; ex[0] = __builtin_amdgcn_exp2f(v[0]); ex[1] = __builtin_amdgcn_exp2f(v[1]);
;           sum2 += ex;
;           x.u[r >> 1] = pk2(ex[0], ex[1]);
;         }
;         lsum += sum2[0] + sum2[1];
;         return x.b;
;       };
;       qk(0);
;       pf[0][0] = sm8(S0, 0, nmc[0], ls[0]); pf[0][1] = sm8(S0, 8, nmc[0], ls[0]);
;       pf[0][2] = sm8(S1, 0, nmc[0], ls[0]); pf[0][3] = sm8(S1, 8, nmc[0], ls[0]);
;       qk(1);
;       if (!SAMPLE || t + 1 < ntiles) gloadV(tn);
; #pragma unroll
;       for (int sl = 0; sl < 4; ++sl) {
; #pragma unroll
;         for (int e = 0; e < 4; ++e) {
;           const bf16x8 vf = tr8(Vs, AV_B, sl * 16, e * 32, lane);
;           O1[e] = mfma32(vf, pf[0][sl], O1[e]);
;         }
;         pf[1][sl] = sm8(sl < 2 ? S0 : S1, (sl & 1) * 8, nmc[1], ls[1]);
	v_mfma_f32_32x32x16_bf16 a[128:143], v[100:103], v[44:47], a[128:143]
	ds_read_b64_tr_b16 v[100:101], v108 offset:17472
	ds_read_b64_tr_b16 v[122:123], v108 offset:17536
	ds_read_b64_tr_b16 v[142:143], v108 offset:17600
	ds_read_b64_tr_b16 v[102:103], v108 offset:20032
	ds_read_b64_tr_b16 v[124:125], v108 offset:20096
	ds_read_b64_tr_b16 v[144:145], v108 offset:20160
	v_mfma_f32_32x32x16_bf16 v[226:241], v[96:99], v[44:47], v[226:241]
	s_waitcnt lgkmcnt(6)
	v_cvt_pk_bf16_f32 v93, v94, v95
	v_cvt_pk_bf16_f32 v94, v88, v89
	v_cvt_pk_bf16_f32 v95, v90, v91
	v_fma_f32 v88, v186, s52, v48
	v_fma_f32 v89, v187, s52, v49
	v_mfma_f32_32x32x16_bf16 a[0:15], v[116:119], v[92:95], a[0:15]
	ds_read_b64_tr_b16 v[146:147], v108 offset:22528
	ds_read_b64_tr_b16 v[148:149], v108 offset:25088
	s_waitcnt lgkmcnt(4)
	v_add_f32_e32 v62, v90, v62
	v_add_f32_e32 v63, v91, v63
	v_exp_f32_e32 v88, v88
	v_mfma_f32_32x32x16_bf16 a[32:47], v[100:103], v[92:95], a[32:47]
	ds_read_b64_tr_b16 v[150:151], v108 offset:22592
	ds_read_b64_tr_b16 v[154:155], v108 offset:22656
	ds_read_b64_tr_b16 v[158:159], v108 offset:22720
	ds_read_b64_tr_b16 v[152:153], v108 offset:25152
	ds_read_b64_tr_b16 v[156:157], v108 offset:25216
	ds_read_b64_tr_b16 v[160:161], v108 offset:25280
	s_waitcnt lgkmcnt(9)
	v_mfma_f32_32x32x16_bf16 a[64:79], v[122:125], v[92:95], a[64:79]
	s_waitcnt lgkmcnt(8)
	v_exp_f32_e32 v89, v89
	v_fma_f32 v90, v188, s52, v48
	v_fma_f32 v91, v189, s52, v49
	v_exp_f32_e32 v90, v90
	v_mfma_f32_32x32x16_bf16 a[96:111], v[142:145], v[92:95], a[96:111]
	ds_read_b64_tr_b16 v[162:163], v108 offset:27648
	ds_read_b64_tr_b16 v[164:165], v108 offset:30208
	s_waitcnt lgkmcnt(8)
	v_exp_f32_e32 v91, v91
	v_add_f32_e64 v96, v88, 0
	v_cvt_pk_bf16_f32 v88, v88, v89
	v_add_f32_e32 v96, v90, v96
	v_add_f32_e32 v97, v91, v89
	v_exp_f32_e32 v98, v64
	v_exp_f32_e32 v99, v65
	v_cvt_pk_bf16_f32 v89, v90, v91
	v_cvt_pk_bf16_f32 v90, v66, v67
	v_cvt_pk_bf16_f32 v91, v98, v99
	v_add_f32_e32 v64, v66, v96
	v_add_f32_e32 v65, v67, v97
	v_mfma_f32_32x32x16_bf16 a[0:15], v[146:149], v[88:91], a[0:15]
	ds_read_b64_tr_b16 v[166:167], v108 offset:27712
	ds_read_b64_tr_b16 v[170:171], v108 offset:27776
	ds_read_b64_tr_b16 v[174:175], v108 offset:27840
	ds_read_b64_tr_b16 v[168:169], v108 offset:30272
	ds_read_b64_tr_b16 v[172:173], v108 offset:30336
	ds_read_b64_tr_b16 v[176:177], v108 offset:30400
	s_waitcnt lgkmcnt(10)
	v_mfma_f32_32x32x16_bf16 a[32:47], v[150:153], v[88:91], a[32:47]
	s_waitcnt lgkmcnt(9)
	v_fma_f32 v66, v210, s52, v48
	v_fma_f32 v67, v211, s52, v49
	v_exp_f32_e32 v66, v66
	v_exp_f32_e32 v67, v67
	v_mfma_f32_32x32x16_bf16 a[64:79], v[154:157], v[88:91], a[64:79]
	s_waitcnt lgkmcnt(8)
	v_add_f32_e32 v64, v98, v64
	v_add_f32_e32 v65, v99, v65
	v_fma_f32 v98, v216, s52, v48
	v_fma_f32 v99, v217, s52, v49
	v_fma_f32 v92, v212, s52, v48
	v_mfma_f32_32x32x16_bf16 a[96:111], v[158:161], v[88:91], a[96:111]
	s_waitcnt lgkmcnt(6)
	v_fma_f32 v93, v213, s52, v49
	v_exp_f32_e32 v98, v98
	v_exp_f32_e32 v94, v92
	v_exp_f32_e32 v95, v93
	v_cvt_pk_bf16_f32 v92, v66, v67
	v_exp_f32_e32 v99, v99
	v_add_f32_e64 v66, v94, v66
	v_add_f32_e64 v67, v95, v67
	v_fma_f32 v96, v214, s52, v48
	v_fma_f32 v97, v215, s52, v49
	v_exp_f32_e32 v96, v96
	v_exp_f32_e32 v97, v97
	v_cvt_pk_bf16_f32 v93, v94, v95
	v_cvt_pk_bf16_f32 v94, v96, v97
	v_cvt_pk_bf16_f32 v95, v98, v99
	v_exp_f32_e32 v75, v75
	v_fma_f32 v70, v222, s52, v48
	v_mfma_f32_32x32x16_bf16 a[0:15], v[162:165], v[92:95], a[0:15]
	ds_read_b64_tr_b16 v[178:179], v108 offset:32768
	ds_read_b64_tr_b16 v[180:181], v108 offset:35328
	ds_read_b64_tr_b16 v[182:183], v108 offset:32832
	ds_read_b64_tr_b16 v[186:187], v108 offset:32896
	ds_read_b64_tr_b16 v[190:191], v108 offset:32960
	ds_read_b64_tr_b16 v[184:185], v108 offset:35392
	ds_read_b64_tr_b16 v[188:189], v108 offset:35456
	ds_read_b64_tr_b16 v[192:193], v108 offset:35520
	s_waitcnt lgkmcnt(10)
	v_mfma_f32_32x32x16_bf16 a[32:47], v[166:169], v[92:95], a[32:47]
	s_waitcnt lgkmcnt(9)
	v_fma_f32 v71, v223, s52, v49
	v_exp_f32_e32 v88, v72
	v_exp_f32_e32 v89, v73
	v_mfma_f32_32x32x16_bf16 a[64:79], v[170:173], v[92:95], a[64:79]
	s_waitcnt lgkmcnt(8)
	v_exp_f32_e32 v70, v70
	v_exp_f32_e32 v71, v71
	v_fma_f32 v68, v224, s52, v48
	v_mfma_f32_32x32x16_bf16 a[96:111], v[174:177], v[92:95], a[96:111]
	s_waitcnt lgkmcnt(6)
	v_fma_f32 v69, v225, s52, v49
	v_cvt_pk_bf16_f32 v72, v74, v75
	v_add_f32_e64 v74, v88, v74
	v_add_f32_e64 v75, v89, v75
	v_exp_f32_e32 v90, v68
	v_exp_f32_e32 v91, v69
	v_add_f32_e32 v68, v70, v74
	v_add_f32_e32 v69, v71, v75
	v_cvt_pk_bf16_f32 v74, v70, v71
	v_cvt_pk_bf16_f32 v73, v88, v89
	v_cvt_pk_bf16_f32 v75, v90, v91
	v_add_f32_e32 v66, v96, v66
	v_add_f32_e32 v67, v97, v67
	v_mfma_f32_32x32x16_bf16 a[0:15], v[178:181], v[72:75], a[0:15]
	s_waitcnt lgkmcnt(2)
	v_add_f32_e64 v66, v98, v66
	v_add_f32_e64 v67, v99, v67
	v_fma_f32 v98, v226, s52, v52
	v_fma_f32 v99, v227, s52, v53
	v_fma_f32 v96, v228, s52, v52
	v_mfma_f32_32x32x16_bf16 a[32:47], v[182:185], v[72:75], a[32:47]
	s_waitcnt lgkmcnt(1)
	v_fma_f32 v97, v229, s52, v53
	v_fma_f32 v70, v232, s52, v52
	v_fma_f32 v71, v233, s52, v53
	v_exp_f32_e32 v104, v98
	v_mfma_f32_32x32x16_bf16 a[64:79], v[186:189], v[72:75], a[64:79]
	s_waitcnt lgkmcnt(0)
; DEV f32x16 mfma32(bf16x8 a, bf16x8 b, f32x16 c) { return __builtin_amdgcn_mfma_f32_32x32x16_bf16(a, b, c, 0, 0, 0); }
; template <bool SAMPLE>
; DEV void attn_unit(CParams& p, int layer, int unit, float lam, float lam_init, char* lds, const int swave) {
;     ...
; #pragma unroll
;       for (int sl = 0; sl < 4; ++sl) {
; #pragma unroll
;         for (int e = 0; e < 4; ++e) {
;           const bf16x8 vf = tr8(Vs, AV_B, sl * 16, e * 32, lane);
;           O1[e] = mfma32(vf, pf[0][sl], O1[e]);
;         }
;         pf[1][sl] = sm8(sl < 2 ? S0 : S1, (sl & 1) * 8, nmc[1], ls[1]);
;       }
; #pragma unroll
;       for (int sl = 0; sl < 4; ++sl)
; #pragma unroll
;         for (int e = 0; e < 4; ++e) {
;           const bf16x8 vf = tr8(Vs, AV_B, sl * 16, e * 32, lane);
;           O2[e] = mfma32(vf, pf[1][sl], O2[e]);
;         }
;     }
;     if (t >= my_tiles && (!SAMPLE || t + 1 < ntiles)) gloadV(tn);
;     if (!SAMPLE || t + 1 < ntiles) lwrite((t + 1) & 1);
	v_fma_f32 v94, v230, s52, v52
	v_fma_f32 v95, v231, s52, v53
	v_exp_f32_e32 v105, v99
	v_exp_f32_e32 v106, v96
	v_mfma_f32_32x32x16_bf16 a[96:111], v[190:193], v[72:75], a[96:111]
	v_exp_f32_e32 v107, v97
	v_exp_f32_e32 v108, v94
	v_exp_f32_e32 v109, v95
	v_exp_f32_e32 v74, v70
	v_exp_f32_e32 v75, v71
	v_cvt_pk_bf16_f32 v70, v104, v105
	v_cvt_pk_bf16_f32 v71, v106, v107
	v_cvt_pk_bf16_f32 v72, v108, v109
	v_cvt_pk_bf16_f32 v73, v74, v75
	v_add_f32_e32 v68, v90, v68
	v_add_f32_e32 v69, v91, v69
	v_mfma_f32_32x32x16_bf16 a[16:31], v[116:119], v[70:73], a[16:31]
	v_fma_f32 v94, v234, s52, v52
	v_fma_f32 v95, v235, s52, v53
	v_fma_f32 v92, v236, s52, v52
	v_fma_f32 v93, v237, s52, v53
	v_fma_f32 v90, v238, s52, v52
	v_fma_f32 v91, v239, s52, v53
	v_mfma_f32_32x32x16_bf16 a[48:63], v[100:103], v[70:73], a[48:63]
	v_exp_f32_e32 v120, v94
	v_exp_f32_e32 v121, v95
	v_accvgpr_read_b32 v133, a133
	v_accvgpr_read_b32 v132, a132
	v_mfma_f32_32x32x16_bf16 a[80:95], v[122:125], v[70:73], a[80:95]
	v_accvgpr_read_b32 v139, a131
	v_accvgpr_read_b32 v138, a130
	v_fma_f32 v132, v132, s52, v52
	v_fma_f32 v133, v133, s52, v53
	v_accvgpr_read_b32 v115, a139
	v_exp_f32_e32 v132, v132
	v_mfma_f32_32x32x16_bf16 a[112:127], v[142:145], v[70:73], a[112:127]
	v_cvt_pk_bf16_f32 v100, v120, v121
	v_exp_f32_e32 v122, v92
	v_exp_f32_e32 v123, v93
	v_exp_f32_e32 v124, v90
	v_exp_f32_e32 v125, v91
	v_cvt_pk_bf16_f32 v101, v122, v123
	v_fma_f32 v70, v240, s52, v52
	v_fma_f32 v71, v241, s52, v53
	v_cvt_pk_bf16_f32 v102, v124, v125
	v_exp_f32_e32 v126, v70
	v_exp_f32_e32 v127, v71
	s_nop 0
	v_cvt_pk_bf16_f32 v103, v126, v127
	v_add_f32_e64 v104, v106, v104
	v_add_f32_e64 v105, v107, v105
	v_mfma_f32_32x32x16_bf16 a[16:31], v[146:149], v[100:103], a[16:31]
	v_accvgpr_read_b32 v106, a128
	v_accvgpr_read_b32 v119, a135
	v_accvgpr_read_b32 v118, a134
	v_accvgpr_read_b32 v107, a129
	v_add_f32_e32 v104, v108, v104
	v_add_f32_e32 v105, v109, v105
	v_mfma_f32_32x32x16_bf16 a[48:63], v[150:153], v[100:103], a[48:63]
	v_fma_f32 v106, v106, s52, v52
	v_fma_f32 v107, v107, s52, v53
	v_fma_f32 v108, v138, s52, v52
	v_fma_f32 v109, v139, s52, v53
	v_exp_f32_e32 v106, v106
	v_mfma_f32_32x32x16_bf16 a[80:95], v[154:157], v[100:103], a[80:95]
	s_andn2_b32 s8, 1, s37
	s_mul_i32 s8, s8, 0x9400
	s_add_i32 s8, s8, 16
	s_waitcnt vmcnt(0)
	v_add3_u32 v54, s8, v77, v76
	ds_write_b128 v54, v[4:7]
	v_add3_u32 v55, s8, v78, v76
	ds_write_b128 v55, v[194:197] offset:17408
	v_mfma_f32_32x32x16_bf16 a[112:127], v[158:161], v[100:103], a[112:127]
	v_add3_u32 v56, s8, v79, v76
	ds_write_b128 v56, v[0:3]
	v_add3_u32 v57, s8, v80, v76
	ds_write_b128 v57, v[198:201] offset:17408
	v_exp_f32_e32 v107, v107
	v_exp_f32_e32 v108, v108
	v_exp_f32_e32 v109, v109
	v_exp_f32_e32 v133, v133
	v_fma_f32 v100, v118, s52, v52
	v_fma_f32 v101, v119, s52, v53
	v_cvt_pk_bf16_f32 v102, v132, v133
	v_exp_f32_e32 v118, v100
	v_exp_f32_e32 v119, v101
	v_cvt_pk_bf16_f32 v100, v106, v107
	v_cvt_pk_bf16_f32 v101, v108, v109
	v_cvt_pk_bf16_f32 v103, v118, v119
	v_add_f32_e32 v74, v74, v104
	v_add_f32_e32 v75, v75, v105
	v_mfma_f32_32x32x16_bf16 a[16:31], v[162:165], v[100:103], a[16:31]
	v_add_f32_e32 v104, v122, v120
	v_add_f32_e32 v105, v123, v121
	v_accvgpr_read_b32 v117, a137
	v_accvgpr_read_b32 v116, a136
	v_add_f32_e64 v104, v124, v104
	v_add_f32_e64 v105, v125, v105
	v_mfma_f32_32x32x16_bf16 a[48:63], v[166:169], v[100:103], a[48:63]
	v_accvgpr_read_b32 v114, a138
	v_add_f32_e64 v120, v126, v104
	v_add_f32_e64 v121, v127, v105
	v_accvgpr_read_b32 v111, a143
	v_accvgpr_read_b32 v110, a142
	v_accvgpr_read_b32 v113, a141
	v_mfma_f32_32x32x16_bf16 a[80:95], v[170:173], v[100:103], a[80:95]
	v_add3_u32 v58, s8, v81, v76
	ds_write_b128 v58, v[12:15]
	v_add3_u32 v59, s8, v82, v76
	ds_write_b128 v59, v[202:205] offset:17408
	v_accvgpr_read_b32 v112, a140
	v_add_f32_e64 v104, v108, v106
	v_mfma_f32_32x32x16_bf16 a[112:127], v[174:177], v[100:103], a[112:127]
	v_add3_u32 v60, s8, v83, v76
	ds_write_b128 v60, v[8:11]
	v_add3_u32 v61, s8, v84, v76
	ds_write_b128 v61, v[206:209] offset:17408
	v_add_f32_e64 v105, v109, v107
	v_fma_f32 v112, v112, s52, v52
	v_fma_f32 v113, v113, s52, v53
	v_add_f32_e32 v104, v132, v104
	v_add_f32_e32 v105, v133, v105
	v_exp_f32_e32 v112, v112
	v_exp_f32_e32 v113, v113
	v_fma_f32 v106, v116, s52, v52
	v_fma_f32 v107, v117, s52, v53
	v_exp_f32_e32 v106, v106
	v_exp_f32_e32 v107, v107
	v_fma_f32 v108, v114, s52, v52
	v_fma_f32 v109, v115, s52, v53
	v_add_f32_e64 v114, v118, v104
	v_add_f32_e64 v115, v119, v105
	v_exp_f32_e32 v108, v108
	v_exp_f32_e32 v109, v109
	v_add_f32_e64 v116, v106, 0
	v_add_f32_e64 v117, v107, 0
	v_cvt_pk_bf16_f32 v104, v106, v107
	v_add_f32_e32 v106, v108, v116
	v_add_f32_e32 v107, v109, v117
	v_cvt_pk_bf16_f32 v105, v108, v109
	v_fma_f32 v100, v110, s52, v52
	v_fma_f32 v101, v111, s52, v53
	v_add_f32_e64 v102, v112, v106
	v_add_f32_e64 v103, v113, v107
	v_exp_f32_e32 v100, v100
	v_exp_f32_e32 v101, v101
	v_cvt_pk_bf16_f32 v106, v112, v113
	v_cvt_pk_bf16_f32 v107, v100, v101
	v_add_f32_e64 v100, v100, v102
	v_add_f32_e64 v101, v101, v103
	v_mfma_f32_32x32x16_bf16 a[16:31], v[178:181], v[104:107], a[16:31]
	v_add_f32_e32 v62, v62, v63
	v_add_f32_e32 v74, v74, v75
	v_add_f32_e32 v64, v64, v65
	v_add_f32_e32 v120, v120, v121
	v_add_f32_e32 v66, v66, v67
	v_add_f32_e32 v114, v114, v115
	v_mfma_f32_32x32x16_bf16 a[48:63], v[182:185], v[104:107], a[48:63]
	v_add_f32_e32 v68, v68, v69
	v_add_f32_e32 v100, v100, v101
	v_add_f32_e32 v62, v130, v62
	v_add_f32_e32 v74, v131, v74
	v_add_f32_e32 v62, v64, v62
	v_add_f32_e32 v74, v120, v74
	v_mfma_f32_32x32x16_bf16 a[80:95], v[186:189], v[104:107], a[80:95]
	v_add_f32_e32 v62, v66, v62
	v_add_f32_e32 v74, v114, v74
	v_add_f32_e32 v130, v68, v62
	v_add_f32_e32 v131, v100, v74
	v_mfma_f32_32x32x16_bf16 a[112:127], v[190:193], v[104:107], a[112:127]
	s_branch .Lattn_tail
; template <bool SAMPLE>
; DEV void attn_unit(CParams& p, int layer, int unit, float lam, float lam_init, char* lds, const int swave) {
;     ...
;   auto kbase = [&](int t, int i, unsigned& voff, size_t& vdelta) -> const char* {
;     if (sample && t < 32) { voff = voffC; vdelta = W_VC - W_KC; return ws + W_KC + ((size_t)(b * 2048 + t * 64 + 16 * i) * 512 + head * 128) * 2; }
;     voff = voffP; vdelta = (size_t)(C_V - C_K) * 2;
;     if (sample) return (const char*)proj + ((size_t)(TP + b * 16) * PW + C_K + head * 128) * 2;
;     return (const char*)proj + ((size_t)(b * 16384 + t * 64 + 16 * i) * PW + C_K + head * 128) * 2;
;   };
;   auto gloadK = [&](int t) {
; #pragma unroll
;     for (int i = 0; i < 4; ++i) { unsigned voff; size_t vd; const char* kb = kbase(t, i, voff, vd); rk[i] = *(const u32x4*)(kb + voff); }
;   };
;   auto gloadV = [&](int t) {
; #pragma unroll
;     for (int i = 0; i < 4; ++i) { unsigned voff; size_t vd; const char* kb = kbase(t, i, voff, vd); rv[i] = *(const u32x4*)(kb + vd + voff); }
;   };
;   auto lwrite = [&](int buf) {
;     char* ks_ = lds + buf * A_BUF; char* vs_ = ks_ + A_KT;
; #pragma unroll
;     for (int i = 0; i < 4; ++i) {
;       const int r = krow + 16 * i;
;       *(u32x4*)(ks_ + r * AK_B + kch * 16) = rk[i];
;       *(u32x4*)(vs_ + r * AV_B + kch * 16) = rv[i];
;     }
;   };
;     ...
;     if (t >= my_tiles && (!SAMPLE || t + 1 < ntiles)) gloadV(tn);
;     if (!SAMPLE || t + 1 < ntiles) lwrite((t + 1) & 1);
.LBB0_245:
	s_lshl_b32 s38, s100, 6
	s_add_i32 s8, s38, s28
	s_mul_hi_i32 s9, s8, 0xc00
	s_mulk_i32 s8, 0xc00
	s_or_b64 s[8:9], s[8:9], s[2:3]
	v_lshl_add_u64 v[54:55], s[8:9], 1, v[50:51]
	s_add_i32 s8, s30, s38
	s_mul_hi_i32 s9, s8, 0xc00
	s_mulk_i32 s8, 0xc00
	s_or_b64 s[8:9], s[8:9], s[2:3]
	v_lshl_add_u64 v[56:57], s[8:9], 1, v[50:51]
	s_add_i32 s8, s31, s38
	s_mul_hi_i32 s9, s8, 0xc00
	s_mulk_i32 s8, 0xc00
	s_or_b64 s[8:9], s[8:9], s[2:3]
	v_lshl_add_u64 v[58:59], s[8:9], 1, v[50:51]
	s_add_i32 s8, s34, s38
	s_mul_hi_i32 s9, s8, 0xc00
	s_mulk_i32 s8, 0xc00
	s_or_b64 s[8:9], s[8:9], s[2:3]
	global_load_dwordx4 v[4:7], v[54:55], off
	global_load_dwordx4 v[0:3], v[56:57], off
	v_lshl_add_u64 v[60:61], s[8:9], 1, v[50:51]
	global_load_dwordx4 v[12:15], v[58:59], off
	global_load_dwordx4 v[8:11], v[60:61], off
	global_load_dwordx4 v[194:197], v[54:55], off offset:1024
	global_load_dwordx4 v[198:201], v[56:57], off offset:1024
	global_load_dwordx4 v[202:205], v[58:59], off offset:1024
	global_load_dwordx4 v[206:209], v[60:61], off offset:1024
	s_andn2_b32 s8, 1, s37
	s_mul_i32 s8, s8, 0x9400
	s_add_i32 s8, s8, 16
	s_waitcnt vmcnt(0)
	v_add3_u32 v54, s8, v77, v76
	ds_write_b128 v54, v[4:7]
	v_add3_u32 v55, s8, v78, v76
	ds_write_b128 v55, v[194:197] offset:17408
	v_add3_u32 v56, s8, v79, v76
	ds_write_b128 v56, v[0:3]
	v_add3_u32 v57, s8, v80, v76
	ds_write_b128 v57, v[198:201] offset:17408
	v_add3_u32 v58, s8, v81, v76
	ds_write_b128 v58, v[12:15]
	v_add3_u32 v59, s8, v82, v76
	ds_write_b128 v59, v[202:205] offset:17408
	v_add3_u32 v60, s8, v83, v76
	ds_write_b128 v60, v[8:11]
	v_add3_u32 v61, s8, v84, v76
	ds_write_b128 v61, v[206:209] offset:17408

; DEV float shx(float v, int o, int lane) { return __builtin_bit_cast(float, __builtin_amdgcn_ds_bpermute((lane ^ o) << 2, __builtin_bit_cast(int, v))); }
; template <bool SAMPLE>
; DEV void attn_unit(CParams& p, int layer, int unit, float lam, float lam_init, char* lds, const int swave) {
;     ...
;   if (my_tiles > 0) {
;     const float l1 = ls[0] + shx(ls[0], 32, lane), l2 = ls[1] + shx(ls[1], 32, lane);
;     const float i1 = 1.f / l1, i2 = lam / l2;
;     float s = 0.f;
; #pragma unroll
;     for (int e = 0; e < 4; ++e)
; #pragma unroll
;       for (int r = 0; r < 16; ++r) { const float o = O1[e][r] * i1 - O2[e][r] * i2; O1[e][r] = o; s += o * o; }
;     s += shx(s, 32, lane);
;     const float rs = rsqrtf(s * (1.f / 128.f) + EPS) * (1.f - lam_init);
.LBB0_249:
	v_mov_b32_e32 v240, v244
	v_mov_b32_e32 v241, 0
	ds_bpermute_b32 v80, v135, v130
	ds_bpermute_b32 v132, v135, v131
	v_accvgpr_read_b32 v16, a112
	v_accvgpr_read_b32 v127, a31
	v_accvgpr_read_b32 v0, a96
	s_waitcnt lgkmcnt(1)
	v_add_f32_e32 v130, v130, v80
	v_div_scale_f32 v133, s[2:3], v130, v130, 1.0
	v_rcp_f32_e32 v136, v133
	s_waitcnt lgkmcnt(0)
	v_add_f32_e32 v131, v131, v132
	v_accvgpr_read_b32 v111, a15
	v_accvgpr_read_b32 v18, a114
	v_fma_f32 v132, -v133, v136, 1.0
	v_fmac_f32_e32 v136, v132, v136
	v_div_scale_f32 v132, vcc, 1.0, v130, 1.0
	v_mul_f32_e32 v138, v132, v136
	v_fma_f32 v139, -v133, v138, v132
	v_fmac_f32_e32 v138, v139, v136
	v_fma_f32 v132, -v133, v138, v132
	v_div_scale_f32 v133, s[2:3], v131, v131, v137
	v_rcp_f32_e32 v139, v133
	v_div_fmas_f32 v132, v132, v136, v138
	v_div_fixup_f32 v136, v132, v130, 1.0
	v_accvgpr_read_b32 v19, a115
	v_fma_f32 v130, -v133, v139, 1.0
	v_fmac_f32_e32 v139, v130, v139
	v_div_scale_f32 v130, vcc, v137, v131, v137
	v_mul_f32_e32 v132, v130, v139
	v_fma_f32 v138, -v133, v132, v130
	v_fmac_f32_e32 v132, v138, v139
	v_fma_f32 v130, -v133, v132, v130
	v_div_fmas_f32 v130, v130, v139, v132
	v_accvgpr_read_b32 v113, a17
	v_accvgpr_read_b32 v112, a16
	v_div_fixup_f32 v138, v130, v131, v137
	v_accvgpr_read_b32 v2, a98
	v_accvgpr_read_b32 v3, a99
	v_accvgpr_read_b32 v97, a1
	v_accvgpr_read_b32 v96, a0
	v_accvgpr_read_b32 v17, a113
	v_accvgpr_read_b32 v28, a124
	v_accvgpr_read_b32 v29, a125
	v_accvgpr_read_b32 v115, a19
	v_accvgpr_read_b32 v114, a18
	s_lshl_b32 s2, s45, 2
	v_pk_mul_f32 v[112:113], v[112:113], v[138:139] op_sel_hi:[1,0]
	v_pk_mul_f32 v[18:19], v[18:19], v[138:139] op_sel_hi:[1,0]
	v_accvgpr_read_b32 v1, a97
	v_accvgpr_read_b32 v12, a108
	v_accvgpr_read_b32 v13, a109
	v_accvgpr_read_b32 v99, a3
	v_accvgpr_read_b32 v98, a2
	v_accvgpr_read_b32 v22, a118
	v_accvgpr_read_b32 v23, a119
	v_accvgpr_read_b32 v30, a126
	v_accvgpr_read_b32 v31, a127
	v_accvgpr_read_b32 v119, a23
	v_accvgpr_read_b32 v118, a22
	v_pk_mul_f32 v[28:29], v[28:29], v[138:139] op_sel_hi:[1,0]
	s_add_u32 s2, s4, s2
	v_pk_mul_f32 v[114:115], v[114:115], v[138:139] op_sel_hi:[1,0]
	v_pk_fma_f32 v[112:113], v[96:97], v[136:137], v[112:113] op_sel_hi:[1,0,1] neg_lo:[0,0,1] neg_hi:[0,0,1]
	v_pk_fma_f32 v[18:19], v[2:3], v[136:137], v[18:19] op_sel_hi:[1,0,1] neg_lo:[0,0,1] neg_hi:[0,0,1]
	v_pk_mul_f32 v[2:3], v[16:17], v[138:139] op_sel_hi:[1,0]
	v_accvgpr_read_b32 v6, a102
	v_accvgpr_read_b32 v7, a103
	v_accvgpr_read_b32 v14, a110
	v_accvgpr_read_b32 v15, a111
	v_accvgpr_read_b32 v103, a7
	v_accvgpr_read_b32 v102, a6
	v_accvgpr_read_b32 v24, a120
	v_accvgpr_read_b32 v25, a121
	v_accvgpr_read_b32 v117, a21
	v_accvgpr_read_b32 v116, a20
	v_pk_fma_f32 v[28:29], v[12:13], v[136:137], v[28:29] op_sel_hi:[1,0,1] neg_lo:[0,0,1] neg_hi:[0,0,1]
	v_pk_mul_f32 v[12:13], v[30:31], v[138:139] op_sel_hi:[1,0]
	s_addc_u32 s3, s5, 0
	v_pk_fma_f32 v[98:99], v[98:99], v[136:137], v[114:115] op_sel_hi:[1,0,1] neg_lo:[0,0,1] neg_hi:[0,0,1]
	v_pk_mul_f32 v[144:145], v[112:113], v[112:113]
	v_pk_mul_f32 v[96:97], v[118:119], v[138:139] op_sel_hi:[1,0]
	v_pk_fma_f32 v[16:17], v[0:1], v[136:137], v[2:3] op_sel_hi:[1,0,1] neg_lo:[0,0,1] neg_hi:[0,0,1]
	v_pk_mul_f32 v[0:1], v[22:23], v[138:139] op_sel_hi:[1,0]
	v_accvgpr_read_b32 v101, a5
	v_accvgpr_read_b32 v100, a4
	v_pk_fma_f32 v[30:31], v[14:15], v[136:137], v[12:13] op_sel_hi:[1,0,1] neg_lo:[0,0,1] neg_hi:[0,0,1]
	global_load_dwordx4 v[12:15], v240, s[2:3]
	v_pk_mul_f32 v[142:143], v[98:99], v[98:99]
	v_pk_fma_f32 v[96:97], v[102:103], v[136:137], v[96:97] op_sel_hi:[1,0,1] neg_lo:[0,0,1] neg_hi:[0,0,1]
	v_pk_mul_f32 v[102:103], v[116:117], v[138:139] op_sel_hi:[1,0]
	v_pk_fma_f32 v[0:1], v[6:7], v[136:137], v[0:1] op_sel_hi:[1,0,1] neg_lo:[0,0,1] neg_hi:[0,0,1]
	v_pk_mul_f32 v[6:7], v[24:25], v[138:139] op_sel_hi:[1,0]
	v_add_f32_e32 v24, v144, v145
	v_pk_fma_f32 v[114:115], v[100:101], v[136:137], v[102:103] op_sel_hi:[1,0,1] neg_lo:[0,0,1] neg_hi:[0,0,1]
	v_add_f32_e32 v24, v142, v24
	v_pk_mul_f32 v[116:117], v[114:115], v[114:115]
	v_add_f32_e32 v24, v143, v24
	v_accvgpr_read_b32 v121, a25
	v_accvgpr_read_b32 v120, a24
	v_add_f32_e32 v24, v116, v24
	v_accvgpr_read_b32 v105, a9
	v_accvgpr_read_b32 v104, a8
	v_pk_mul_f32 v[118:119], v[96:97], v[96:97]
	v_pk_mul_f32 v[102:103], v[120:121], v[138:139] op_sel_hi:[1,0]
	v_add_f32_e32 v24, v117, v24
	v_accvgpr_read_b32 v123, a27
	v_accvgpr_read_b32 v122, a26
	v_pk_fma_f32 v[104:105], v[104:105], v[136:137], v[102:103] op_sel_hi:[1,0,1] neg_lo:[0,0,1] neg_hi:[0,0,1]
	v_add_f32_e32 v24, v118, v24
	v_accvgpr_read_b32 v107, a11
	v_accvgpr_read_b32 v106, a10
	v_pk_mul_f32 v[100:101], v[122:123], v[138:139] op_sel_hi:[1,0]
	v_pk_mul_f32 v[120:121], v[104:105], v[104:105]
	v_add_f32_e32 v24, v119, v24
	v_accvgpr_read_b32 v125, a29
	v_accvgpr_read_b32 v124, a28
	v_pk_fma_f32 v[100:101], v[106:107], v[136:137], v[100:101] op_sel_hi:[1,0,1] neg_lo:[0,0,1] neg_hi:[0,0,1]
	v_add_f32_e32 v24, v120, v24
	v_accvgpr_read_b32 v109, a13
	v_accvgpr_read_b32 v108, a12
	v_pk_mul_f32 v[122:123], v[100:101], v[100:101]
	v_pk_mul_f32 v[106:107], v[124:125], v[138:139] op_sel_hi:[1,0]
	v_add_f32_e32 v24, v121, v24
	v_accvgpr_read_b32 v95, a63
	v_accvgpr_read_b32 v126, a30
	v_pk_fma_f32 v[106:107], v[108:109], v[136:137], v[106:107] op_sel_hi:[1,0,1] neg_lo:[0,0,1] neg_hi:[0,0,1]
	v_add_f32_e32 v24, v122, v24
	v_accvgpr_read_b32 v79, a47
	v_accvgpr_read_b32 v110, a14
	v_accvgpr_read_b32 v83, a51
	v_accvgpr_read_b32 v82, a50
	v_pk_mul_f32 v[102:103], v[126:127], v[138:139] op_sel_hi:[1,0]
	v_pk_mul_f32 v[108:109], v[106:107], v[106:107]
	v_add_f32_e32 v24, v123, v24
; template <bool SAMPLE>
; DEV void attn_unit(CParams& p, int layer, int unit, float lam, float lam_init, char* lds, const int swave) {
;     ...
;     for (int e = 0; e < 4; ++e)
; #pragma unroll
;       for (int r = 0; r < 16; ++r) { const float o = O1[e][r] * i1 - O2[e][r] * i2; O1[e][r] = o; s += o * o; }
	v_accvgpr_read_b32 v67, a35
	v_accvgpr_read_b32 v66, a34
	v_accvgpr_read_b32 v81, a49
	v_accvgpr_read_b32 v80, a48
	v_pk_fma_f32 v[102:103], v[110:111], v[136:137], v[102:103] op_sel_hi:[1,0,1] neg_lo:[0,0,1] neg_hi:[0,0,1]
	v_pk_mul_f32 v[82:83], v[82:83], v[138:139] op_sel_hi:[1,0]
	v_add_f32_e32 v24, v108, v24
	v_accvgpr_read_b32 v65, a33
	v_accvgpr_read_b32 v64, a32
	v_pk_mul_f32 v[110:111], v[102:103], v[102:103]
	v_pk_fma_f32 v[82:83], v[66:67], v[136:137], v[82:83] op_sel_hi:[1,0,1] neg_lo:[0,0,1] neg_hi:[0,0,1]
	v_pk_mul_f32 v[66:67], v[80:81], v[138:139] op_sel_hi:[1,0]
	v_add_f32_e32 v24, v109, v24
	v_pk_fma_f32 v[80:81], v[64:65], v[136:137], v[66:67] op_sel_hi:[1,0,1] neg_lo:[0,0,1] neg_hi:[0,0,1]
	v_add_f32_e32 v24, v110, v24
	v_pk_mul_f32 v[126:127], v[80:81], v[80:81]
	v_add_f32_e32 v24, v111, v24
	v_accvgpr_read_b32 v87, a55
	v_accvgpr_read_b32 v86, a54
	v_accvgpr_read_b32 v85, a53
	v_accvgpr_read_b32 v84, a52
	v_add_f32_e32 v24, v126, v24
	v_accvgpr_read_b32 v71, a39
	v_accvgpr_read_b32 v70, a38
	v_accvgpr_read_b32 v69, a37
	v_accvgpr_read_b32 v68, a36
	v_pk_mul_f32 v[124:125], v[82:83], v[82:83]
	v_pk_mul_f32 v[64:65], v[86:87], v[138:139] op_sel_hi:[1,0]
	v_pk_mul_f32 v[66:67], v[84:85], v[138:139] op_sel_hi:[1,0]
	v_add_f32_e32 v24, v127, v24
	v_pk_fma_f32 v[64:65], v[70:71], v[136:137], v[64:65] op_sel_hi:[1,0,1] neg_lo:[0,0,1] neg_hi:[0,0,1]
	v_pk_fma_f32 v[70:71], v[68:69], v[136:137], v[66:67] op_sel_hi:[1,0,1] neg_lo:[0,0,1] neg_hi:[0,0,1]
	v_add_f32_e32 v24, v124, v24
	v_pk_mul_f32 v[84:85], v[70:71], v[70:71]
	v_add_f32_e32 v24, v125, v24
	v_accvgpr_read_b32 v89, a57
	v_accvgpr_read_b32 v88, a56
	v_add_f32_e32 v24, v84, v24
	v_accvgpr_read_b32 v73, a41
	v_accvgpr_read_b32 v72, a40
	v_pk_mul_f32 v[86:87], v[64:65], v[64:65]
	v_pk_mul_f32 v[68:69], v[88:89], v[138:139] op_sel_hi:[1,0]
	v_add_f32_e32 v24, v85, v24
	v_accvgpr_read_b32 v91, a59
	v_accvgpr_read_b32 v90, a58
	v_pk_fma_f32 v[72:73], v[72:73], v[136:137], v[68:69] op_sel_hi:[1,0,1] neg_lo:[0,0,1] neg_hi:[0,0,1]
	v_add_f32_e32 v24, v86, v24
	v_accvgpr_read_b32 v75, a43
	v_accvgpr_read_b32 v74, a42
	v_pk_mul_f32 v[66:67], v[90:91], v[138:139] op_sel_hi:[1,0]
	v_pk_mul_f32 v[88:89], v[72:73], v[72:73]
	v_add_f32_e32 v24, v87, v24
	v_accvgpr_read_b32 v93, a61
	v_accvgpr_read_b32 v92, a60
	v_pk_fma_f32 v[66:67], v[74:75], v[136:137], v[66:67] op_sel_hi:[1,0,1] neg_lo:[0,0,1] neg_hi:[0,0,1]
	v_add_f32_e32 v24, v88, v24
	v_accvgpr_read_b32 v77, a45
	v_accvgpr_read_b32 v76, a44
	v_pk_mul_f32 v[90:91], v[66:67], v[66:67]
	v_pk_mul_f32 v[74:75], v[92:93], v[138:139] op_sel_hi:[1,0]
	v_add_f32_e32 v24, v89, v24
	v_accvgpr_read_b32 v48, a80
	v_accvgpr_read_b32 v94, a62
	v_pk_fma_f32 v[74:75], v[76:77], v[136:137], v[74:75] op_sel_hi:[1,0,1] neg_lo:[0,0,1] neg_hi:[0,0,1]
	v_add_f32_e32 v24, v90, v24
	v_accvgpr_read_b32 v32, a64
	v_accvgpr_read_b32 v78, a46
	v_accvgpr_read_b32 v50, a82
	v_accvgpr_read_b32 v51, a83
	v_pk_mul_f32 v[68:69], v[94:95], v[138:139] op_sel_hi:[1,0]
	v_pk_mul_f32 v[76:77], v[74:75], v[74:75]
	v_add_f32_e32 v24, v91, v24
	v_accvgpr_read_b32 v34, a66
	v_accvgpr_read_b32 v35, a67
	v_accvgpr_read_b32 v49, a81
	v_pk_fma_f32 v[68:69], v[78:79], v[136:137], v[68:69] op_sel_hi:[1,0,1] neg_lo:[0,0,1] neg_hi:[0,0,1]
	v_pk_mul_f32 v[50:51], v[50:51], v[138:139] op_sel_hi:[1,0]
	v_add_f32_e32 v24, v76, v24
	v_accvgpr_read_b32 v33, a65
	v_pk_mul_f32 v[78:79], v[68:69], v[68:69]
	v_pk_fma_f32 v[50:51], v[34:35], v[136:137], v[50:51] op_sel_hi:[1,0,1] neg_lo:[0,0,1] neg_hi:[0,0,1]
	v_pk_mul_f32 v[34:35], v[48:49], v[138:139] op_sel_hi:[1,0]
	v_add_f32_e32 v24, v77, v24
	v_pk_fma_f32 v[48:49], v[32:33], v[136:137], v[34:35] op_sel_hi:[1,0,1] neg_lo:[0,0,1] neg_hi:[0,0,1]
	v_add_f32_e32 v24, v78, v24
	v_pk_mul_f32 v[94:95], v[48:49], v[48:49]
	v_add_f32_e32 v24, v79, v24
	v_accvgpr_read_b32 v52, a84
	v_accvgpr_read_b32 v53, a85
	v_accvgpr_read_b32 v54, a86
	v_accvgpr_read_b32 v55, a87
	v_add_f32_e32 v24, v94, v24
	v_accvgpr_read_b32 v36, a68
	v_accvgpr_read_b32 v37, a69
	v_accvgpr_read_b32 v38, a70
	v_accvgpr_read_b32 v39, a71
	v_pk_mul_f32 v[92:93], v[50:51], v[50:51]
	v_pk_mul_f32 v[32:33], v[54:55], v[138:139] op_sel_hi:[1,0]
	v_pk_mul_f32 v[34:35], v[52:53], v[138:139] op_sel_hi:[1,0]
	v_add_f32_e32 v24, v95, v24
	v_pk_fma_f32 v[32:33], v[38:39], v[136:137], v[32:33] op_sel_hi:[1,0,1] neg_lo:[0,0,1] neg_hi:[0,0,1]
	v_pk_fma_f32 v[38:39], v[36:37], v[136:137], v[34:35] op_sel_hi:[1,0,1] neg_lo:[0,0,1] neg_hi:[0,0,1]
	v_add_f32_e32 v24, v92, v24
	v_pk_mul_f32 v[52:53], v[38:39], v[38:39]
	v_add_f32_e32 v24, v93, v24
	v_accvgpr_read_b32 v56, a88
	v_accvgpr_read_b32 v57, a89
	v_add_f32_e32 v24, v52, v24
	v_accvgpr_read_b32 v40, a72
	v_accvgpr_read_b32 v41, a73
	v_pk_mul_f32 v[54:55], v[32:33], v[32:33]
	v_pk_mul_f32 v[36:37], v[56:57], v[138:139] op_sel_hi:[1,0]
	v_add_f32_e32 v24, v53, v24
	v_accvgpr_read_b32 v58, a90
	v_accvgpr_read_b32 v59, a91
	v_pk_fma_f32 v[40:41], v[40:41], v[136:137], v[36:37] op_sel_hi:[1,0,1] neg_lo:[0,0,1] neg_hi:[0,0,1]
	v_add_f32_e32 v24, v54, v24
	v_accvgpr_read_b32 v42, a74
	v_accvgpr_read_b32 v43, a75
	v_pk_mul_f32 v[34:35], v[58:59], v[138:139] op_sel_hi:[1,0]
	v_pk_mul_f32 v[56:57], v[40:41], v[40:41]
	v_add_f32_e32 v24, v55, v24
	v_accvgpr_read_b32 v60, a92
	v_accvgpr_read_b32 v61, a93
	v_pk_fma_f32 v[34:35], v[42:43], v[136:137], v[34:35] op_sel_hi:[1,0,1] neg_lo:[0,0,1] neg_hi:[0,0,1]
	v_add_f32_e32 v24, v56, v24
	v_accvgpr_read_b32 v44, a76
	v_accvgpr_read_b32 v45, a77
	v_pk_mul_f32 v[58:59], v[34:35], v[34:35]
	v_pk_mul_f32 v[42:43], v[60:61], v[138:139] op_sel_hi:[1,0]
	v_add_f32_e32 v24, v57, v24
	v_accvgpr_read_b32 v62, a94
; DEV uint32_t pk2(float lo, float hi) { f32x2 v; v[0] = lo; v[1] = hi; bf16v2 b = __builtin_convertvector(v, bf16v2); return __builtin_bit_cast(uint32_t, b); }
; DEV float shx(float v, int o, int lane) { return __builtin_bit_cast(float, __builtin_amdgcn_ds_bpermute((lane ^ o) << 2, __builtin_bit_cast(int, v))); }
; template <bool SAMPLE>
; DEV void attn_unit(CParams& p, int layer, int unit, float lam, float lam_init, char* lds, const int swave) {
;     ...
;     const float l1 = ls[0] + shx(ls[0], 32, lane), l2 = ls[1] + shx(ls[1], 32, lane);
;     const float i1 = 1.f / l1, i2 = lam / l2;
;     float s = 0.f;
; #pragma unroll
;     for (int e = 0; e < 4; ++e)
; #pragma unroll
;       for (int r = 0; r < 16; ++r) { const float o = O1[e][r] * i1 - O2[e][r] * i2; O1[e][r] = o; s += o * o; }
;     s += shx(s, 32, lane);
;     const float rs = rsqrtf(s * (1.f / 128.f) + EPS) * (1.f - lam_init);
;     const float* g = p.in[24] + layer * 128;
;     const bool valid = !sample || lr < 16;
;     if (valid) {
;       bf16_t* orow = (bf16_t*)(ws + W_MIX) + (size_t)qrow * DM + 512 + head * 128;
; #pragma unroll
;       for (int e = 0; e < 4; ++e)
; #pragma unroll
;         for (int gq = 0; gq < 4; ++gq) {
;           const int ee = e * 32 + 8 * gq + 4 * hh;
;           const f32x4 gv = *(const f32x4*)(g + ee);
;           u32x2 pk; pk[0] = pk2(O1[e][4 * gq] * rs * gv[0], O1[e][4 * gq + 1] * rs * gv[1]); pk[1] = pk2(O1[e][4 * gq + 2] * rs * gv[2], O1[e][4 * gq + 3] * rs * gv[3]);
	v_accvgpr_read_b32 v63, a95
	v_pk_fma_f32 v[42:43], v[44:45], v[136:137], v[42:43] op_sel_hi:[1,0,1] neg_lo:[0,0,1] neg_hi:[0,0,1]
	v_add_f32_e32 v24, v58, v24
	v_accvgpr_read_b32 v46, a78
	v_accvgpr_read_b32 v47, a79
	v_pk_mul_f32 v[36:37], v[62:63], v[138:139] op_sel_hi:[1,0]
	v_pk_mul_f32 v[44:45], v[42:43], v[42:43]
	v_add_f32_e32 v24, v59, v24
	v_pk_fma_f32 v[36:37], v[46:47], v[136:137], v[36:37] op_sel_hi:[1,0,1] neg_lo:[0,0,1] neg_hi:[0,0,1]
	v_add_f32_e32 v24, v44, v24
	v_pk_mul_f32 v[46:47], v[36:37], v[36:37]
	v_add_f32_e32 v24, v45, v24
	v_add_f32_e32 v24, v46, v24
	v_pk_mul_f32 v[62:63], v[16:17], v[16:17]
	v_add_f32_e32 v24, v47, v24
	v_accvgpr_read_b32 v20, a116
	v_accvgpr_read_b32 v21, a117
	v_add_f32_e32 v24, v62, v24
	v_accvgpr_read_b32 v4, a100
	v_accvgpr_read_b32 v5, a101
	v_pk_mul_f32 v[60:61], v[18:19], v[18:19]
	v_pk_mul_f32 v[2:3], v[20:21], v[138:139] op_sel_hi:[1,0]
	v_add_f32_e32 v24, v63, v24
	v_pk_fma_f32 v[4:5], v[4:5], v[136:137], v[2:3] op_sel_hi:[1,0,1] neg_lo:[0,0,1] neg_hi:[0,0,1]
	v_add_f32_e32 v24, v60, v24
	v_pk_mul_f32 v[20:21], v[4:5], v[4:5]
	v_add_f32_e32 v24, v61, v24
	v_add_f32_e32 v20, v20, v24
	v_accvgpr_read_b32 v8, a104
	v_accvgpr_read_b32 v9, a105
	v_pk_mul_f32 v[22:23], v[0:1], v[0:1]
	v_add_f32_e32 v20, v21, v20
	v_accvgpr_read_b32 v26, a122
	v_accvgpr_read_b32 v27, a123
	v_pk_fma_f32 v[6:7], v[8:9], v[136:137], v[6:7] op_sel_hi:[1,0,1] neg_lo:[0,0,1] neg_hi:[0,0,1]
	v_add_f32_e32 v20, v22, v20
	v_accvgpr_read_b32 v10, a106
	v_accvgpr_read_b32 v11, a107
	v_pk_mul_f32 v[2:3], v[26:27], v[138:139] op_sel_hi:[1,0]
	v_pk_mul_f32 v[8:9], v[6:7], v[6:7]
	v_add_f32_e32 v20, v23, v20
	v_pk_fma_f32 v[2:3], v[10:11], v[136:137], v[2:3] op_sel_hi:[1,0,1] neg_lo:[0,0,1] neg_hi:[0,0,1]
	v_add_f32_e32 v8, v8, v20
	v_pk_mul_f32 v[10:11], v[2:3], v[2:3]
	v_add_f32_e32 v8, v9, v8
	v_add_f32_e32 v8, v10, v8
	v_pk_mul_f32 v[130:131], v[28:29], v[28:29]
	v_add_f32_e32 v8, v11, v8
	v_add_f32_e32 v8, v130, v8
	v_pk_mul_f32 v[132:133], v[30:31], v[30:31]
	v_add_f32_e32 v8, v131, v8
	v_add_f32_e32 v8, v132, v8
	v_add_f32_e32 v10, v133, v8
	ds_bpermute_b32 v11, v135, v10
	v_lshlrev_b64 v[8:9], 11, v[128:129]
	v_lshl_add_u64 v[8:9], s[62:63], 0, v[8:9]
	s_lshl_b32 s34, s22, 1
	v_lshl_add_u64 v[8:9], v[8:9], 0, s[34:35]
	s_waitcnt lgkmcnt(0)
	v_add_f32_e32 v10, v10, v11
	v_fmamk_f32 v10, v10, 0x3c000000, v242
	v_mul_f32_e32 v11, 0x4b800000, v10
	v_cmp_gt_f32_e32 vcc, s25, v10
	s_mov_b32 s6, 0x1a5c4000
	s_nop 0
	v_cndmask_b32_e32 v10, v10, v11, vcc
	v_rsq_f32_e32 v22, v10
	v_lshlrev_b32_e32 v10, 3, v134
	v_mov_b32_e32 v11, v241
	v_lshl_add_u64 v[20:21], v[8:9], 0, v[10:11]
	v_mul_f32_e32 v8, 0x45800000, v22
	v_cndmask_b32_e32 v8, v22, v8, vcc
	v_mul_f32_e32 v22, v141, v8
	v_pk_mul_f32 v[8:9], v[112:113], v[22:23] op_sel_hi:[1,0]
	v_pk_mul_f32 v[10:11], v[98:99], v[22:23] op_sel_hi:[1,0]
	s_waitcnt vmcnt(0)
	v_pk_mul_f32 v[8:9], v[12:13], v[8:9]
	v_pk_mul_f32 v[10:11], v[14:15], v[10:11]
	v_cvt_pk_bf16_f32 v8, v8, v9
	v_cvt_pk_bf16_f32 v9, v10, v11
	v_add_co_u32_e32 v10, vcc, s6, v20
	v_pk_mul_f32 v[14:15], v[114:115], v[22:23] op_sel_hi:[1,0]
	s_nop 0
	v_addc_co_u32_e32 v11, vcc, 0, v21, vcc
	global_store_dwordx2 v[10:11], v[8:9], off offset:3072
	global_load_dwordx4 v[8:11], v240, s[2:3] offset:32
	s_mov_b64 s[6:7], 0x1a5c4c00
	v_lshl_add_u64 v[12:13], v[20:21], 0, s[6:7]
	v_pk_mul_f32 v[20:21], v[100:101], v[22:23] op_sel_hi:[1,0]
	v_pk_mul_f32 v[4:5], v[4:5], v[22:23] op_sel_hi:[1,0]
	v_pk_mul_f32 v[0:1], v[0:1], v[22:23] op_sel_hi:[1,0]
	v_pk_mul_f32 v[2:3], v[2:3], v[22:23] op_sel_hi:[1,0]
	s_waitcnt vmcnt(0)
	v_pk_mul_f32 v[8:9], v[8:9], v[14:15]
	v_pk_mul_f32 v[14:15], v[96:97], v[22:23] op_sel_hi:[1,0]
	v_cvt_pk_bf16_f32 v8, v8, v9
	v_pk_mul_f32 v[10:11], v[10:11], v[14:15]
	v_pk_mul_f32 v[14:15], v[104:105], v[22:23] op_sel_hi:[1,0]
	v_cvt_pk_bf16_f32 v9, v10, v11
	global_store_dwordx2 v[12:13], v[8:9], off offset:16
	global_load_dwordx4 v[8:11], v240, s[2:3] offset:64
	s_waitcnt vmcnt(0)
	v_pk_mul_f32 v[8:9], v[8:9], v[14:15]
	v_pk_mul_f32 v[10:11], v[10:11], v[20:21]
	v_cvt_pk_bf16_f32 v8, v8, v9
	v_cvt_pk_bf16_f32 v9, v10, v11
	global_store_dwordx2 v[12:13], v[8:9], off offset:32
	global_load_dwordx4 v[8:11], v240, s[2:3] offset:96
	v_pk_mul_f32 v[14:15], v[106:107], v[22:23] op_sel_hi:[1,0]
	v_pk_mul_f32 v[20:21], v[102:103], v[22:23] op_sel_hi:[1,0]
	s_waitcnt vmcnt(0)
; DEV uint32_t pk2(float lo, float hi) { f32x2 v; v[0] = lo; v[1] = hi; bf16v2 b = __builtin_convertvector(v, bf16v2); return __builtin_bit_cast(uint32_t, b); }
; template <bool SAMPLE>
; DEV void attn_unit(CParams& p, int layer, int unit, float lam, float lam_init, char* lds, const int swave) {
;     ...
;     if (valid) {
;       bf16_t* orow = (bf16_t*)(ws + W_MIX) + (size_t)qrow * DM + 512 + head * 128;
; #pragma unroll
;       for (int e = 0; e < 4; ++e)
; #pragma unroll
;         for (int gq = 0; gq < 4; ++gq) {
;           const int ee = e * 32 + 8 * gq + 4 * hh;
;           const f32x4 gv = *(const f32x4*)(g + ee);
;           u32x2 pk; pk[0] = pk2(O1[e][4 * gq] * rs * gv[0], O1[e][4 * gq + 1] * rs * gv[1]); pk[1] = pk2(O1[e][4 * gq + 2] * rs * gv[2], O1[e][4 * gq + 3] * rs * gv[3]);
;           *(u32x2*)(orow + ee) = pk;
;         }
	v_pk_mul_f32 v[8:9], v[8:9], v[14:15]
	v_pk_mul_f32 v[10:11], v[10:11], v[20:21]
	v_cvt_pk_bf16_f32 v8, v8, v9
	v_cvt_pk_bf16_f32 v9, v10, v11
	global_store_dwordx2 v[12:13], v[8:9], off offset:48
	global_load_dwordx4 v[8:11], v240, s[2:3] offset:128
	v_pk_mul_f32 v[14:15], v[80:81], v[22:23] op_sel_hi:[1,0]
	v_pk_mul_f32 v[20:21], v[82:83], v[22:23] op_sel_hi:[1,0]
	s_waitcnt vmcnt(0)
	v_pk_mul_f32 v[8:9], v[8:9], v[14:15]
	v_pk_mul_f32 v[10:11], v[10:11], v[20:21]
	v_cvt_pk_bf16_f32 v8, v8, v9
	v_cvt_pk_bf16_f32 v9, v10, v11
	global_store_dwordx2 v[12:13], v[8:9], off offset:64
	global_load_dwordx4 v[8:11], v240, s[2:3] offset:160
	v_pk_mul_f32 v[14:15], v[70:71], v[22:23] op_sel_hi:[1,0]
	v_pk_mul_f32 v[20:21], v[64:65], v[22:23] op_sel_hi:[1,0]
	s_waitcnt vmcnt(0)
	v_pk_mul_f32 v[8:9], v[8:9], v[14:15]
	v_pk_mul_f32 v[10:11], v[10:11], v[20:21]
	v_cvt_pk_bf16_f32 v8, v8, v9
	v_cvt_pk_bf16_f32 v9, v10, v11
	global_store_dwordx2 v[12:13], v[8:9], off offset:80
	global_load_dwordx4 v[8:11], v240, s[2:3] offset:192
	v_pk_mul_f32 v[14:15], v[72:73], v[22:23] op_sel_hi:[1,0]
	v_pk_mul_f32 v[20:21], v[66:67], v[22:23] op_sel_hi:[1,0]
	s_waitcnt vmcnt(0)
	v_pk_mul_f32 v[8:9], v[8:9], v[14:15]
	v_pk_mul_f32 v[10:11], v[10:11], v[20:21]
	v_cvt_pk_bf16_f32 v8, v8, v9
	v_cvt_pk_bf16_f32 v9, v10, v11
	global_store_dwordx2 v[12:13], v[8:9], off offset:96
	global_load_dwordx4 v[8:11], v240, s[2:3] offset:224
	v_pk_mul_f32 v[14:15], v[74:75], v[22:23] op_sel_hi:[1,0]
	v_pk_mul_f32 v[20:21], v[68:69], v[22:23] op_sel_hi:[1,0]
	s_waitcnt vmcnt(0)
	v_pk_mul_f32 v[8:9], v[8:9], v[14:15]
	v_pk_mul_f32 v[10:11], v[10:11], v[20:21]
	v_cvt_pk_bf16_f32 v8, v8, v9
	v_cvt_pk_bf16_f32 v9, v10, v11
	global_store_dwordx2 v[12:13], v[8:9], off offset:112
	global_load_dwordx4 v[8:11], v240, s[2:3] offset:256
	v_pk_mul_f32 v[14:15], v[48:49], v[22:23] op_sel_hi:[1,0]
	v_pk_mul_f32 v[20:21], v[50:51], v[22:23] op_sel_hi:[1,0]
	s_waitcnt vmcnt(0)
	v_pk_mul_f32 v[8:9], v[8:9], v[14:15]
	v_pk_mul_f32 v[10:11], v[10:11], v[20:21]
	v_cvt_pk_bf16_f32 v8, v8, v9
	v_cvt_pk_bf16_f32 v9, v10, v11
	global_store_dwordx2 v[12:13], v[8:9], off offset:128
	global_load_dwordx4 v[8:11], v240, s[2:3] offset:288
	v_pk_mul_f32 v[14:15], v[38:39], v[22:23] op_sel_hi:[1,0]
	v_pk_mul_f32 v[20:21], v[32:33], v[22:23] op_sel_hi:[1,0]
	s_waitcnt vmcnt(0)
	v_pk_mul_f32 v[8:9], v[8:9], v[14:15]
	v_pk_mul_f32 v[10:11], v[10:11], v[20:21]
	v_cvt_pk_bf16_f32 v8, v8, v9
	v_cvt_pk_bf16_f32 v9, v10, v11
	global_store_dwordx2 v[12:13], v[8:9], off offset:144
	global_load_dwordx4 v[8:11], v240, s[2:3] offset:320
	v_pk_mul_f32 v[14:15], v[40:41], v[22:23] op_sel_hi:[1,0]
	v_pk_mul_f32 v[20:21], v[34:35], v[22:23] op_sel_hi:[1,0]
	s_waitcnt vmcnt(0)
	v_pk_mul_f32 v[8:9], v[8:9], v[14:15]
	v_pk_mul_f32 v[10:11], v[10:11], v[20:21]
	v_cvt_pk_bf16_f32 v8, v8, v9
	v_cvt_pk_bf16_f32 v9, v10, v11
	global_store_dwordx2 v[12:13], v[8:9], off offset:160
	global_load_dwordx4 v[8:11], v240, s[2:3] offset:352
	v_pk_mul_f32 v[14:15], v[42:43], v[22:23] op_sel_hi:[1,0]
	v_pk_mul_f32 v[20:21], v[36:37], v[22:23] op_sel_hi:[1,0]
	s_waitcnt vmcnt(0)
	v_pk_mul_f32 v[8:9], v[8:9], v[14:15]
	v_pk_mul_f32 v[10:11], v[10:11], v[20:21]
	v_cvt_pk_bf16_f32 v8, v8, v9
	v_cvt_pk_bf16_f32 v9, v10, v11
	global_store_dwordx2 v[12:13], v[8:9], off offset:176
	global_load_dwordx4 v[8:11], v240, s[2:3] offset:384
	v_pk_mul_f32 v[14:15], v[16:17], v[22:23] op_sel_hi:[1,0]
	v_pk_mul_f32 v[16:17], v[18:19], v[22:23] op_sel_hi:[1,0]
	s_waitcnt vmcnt(0)
	v_pk_mul_f32 v[8:9], v[8:9], v[14:15]
	v_pk_mul_f32 v[10:11], v[10:11], v[16:17]
	v_cvt_pk_bf16_f32 v8, v8, v9
	v_cvt_pk_bf16_f32 v9, v10, v11
	global_store_dwordx2 v[12:13], v[8:9], off offset:192
	global_load_dwordx4 v[8:11], v240, s[2:3] offset:416
	s_waitcnt vmcnt(0)
	v_pk_mul_f32 v[4:5], v[8:9], v[4:5]
	v_pk_mul_f32 v[0:1], v[10:11], v[0:1]
	v_cvt_pk_bf16_f32 v4, v4, v5
	v_cvt_pk_bf16_f32 v5, v0, v1
	global_store_dwordx2 v[12:13], v[4:5], off offset:208
	global_load_dwordx4 v[8:11], v240, s[2:3] offset:448
	v_pk_mul_f32 v[0:1], v[6:7], v[22:23] op_sel_hi:[1,0]
	v_pk_mul_f32 v[4:5], v[28:29], v[22:23] op_sel_hi:[1,0]
	v_pk_mul_f32 v[6:7], v[30:31], v[22:23] op_sel_hi:[1,0]
	s_waitcnt vmcnt(0)
	v_pk_mul_f32 v[0:1], v[8:9], v[0:1]
	v_pk_mul_f32 v[2:3], v[10:11], v[2:3]
	v_cvt_pk_bf16_f32 v0, v0, v1
	v_cvt_pk_bf16_f32 v1, v2, v3
	global_store_dwordx2 v[12:13], v[0:1], off offset:224
	global_load_dwordx4 v[0:3], v240, s[2:3] offset:480
	s_mov_b64 s[2:3], 0
	s_waitcnt vmcnt(0)
	v_pk_mul_f32 v[0:1], v[0:1], v[4:5]
	v_pk_mul_f32 v[2:3], v[2:3], v[6:7]
	v_cvt_pk_bf16_f32 v0, v0, v1
	v_cvt_pk_bf16_f32 v1, v2, v3
	global_store_dwordx2 v[12:13], v[0:1], off offset:240
